# DPP row-rotate + permlane16/32-swap wave all-reduce replaces the 6-round ds_bpermute butterflies in the four row-wise norm/residual loops
# speedup vs baseline: 1.0054x; 1.0054x over previous
.LBB0_113:
	s_ashr_i32 s15, s14, 31
	s_add_i32 s0, s14, 1
	s_ashr_i32 s20, s17, 11
	s_add_i32 s4, s14, 2
	s_add_i32 s8, s14, 3
	s_lshl_b64 s[18:19], s[14:15], 12
	s_ashr_i32 s1, s0, 31
	s_mul_i32 s20, s20, 9
	s_ashr_i32 s5, s4, 31
	s_ashr_i32 s9, s8, 31
	v_lshl_add_u64 v[0:1], v[68:69], 0, s[18:19]
	s_lshl_b64 s[18:19], s[0:1], 12
	s_ashr_i32 s21, s20, 31
	s_lshl_b64 s[26:27], s[4:5], 12
	s_lshl_b64 s[28:29], s[8:9], 12
	v_lshl_add_u64 v[76:77], v[68:69], 0, s[18:19]
	s_lshl_b64 s[18:19], s[20:21], 12
	global_load_dwordx4 v[64:67], v[72:73], off
	global_load_dwordx4 v[36:39], v[0:1], off nt
	global_load_dwordx4 v[20:23], v[0:1], off offset:1024 nt
	global_load_dwordx4 v[16:19], v[0:1], off offset:2048 nt
	s_nop 0
	global_load_dwordx4 v[0:3], v[0:1], off offset:3072 nt
	s_add_u32 s18, s2, s18
	s_addc_u32 s19, s3, s19
	s_add_u32 s20, s18, 0x1000
	v_lshl_add_u64 v[78:79], v[68:69], 0, s[26:27]
	v_lshl_add_u64 v[80:81], v[68:69], 0, s[28:29]
	global_load_dwordx4 v[52:55], v[76:77], off nt
	global_load_dwordx4 v[48:51], v[76:77], off offset:1024 nt
	global_load_dwordx4 v[56:59], v[78:79], off nt
	global_load_dwordx4 v[44:47], v[78:79], off offset:1024 nt
	global_load_dwordx4 v[60:63], v[80:81], off nt
	global_load_dwordx4 v[40:43], v[80:81], off offset:1024 nt
	global_load_dwordx4 v[24:27], v[76:77], off offset:2048 nt
	global_load_dwordx4 v[4:7], v[76:77], off offset:3072 nt
	global_load_dwordx4 v[28:31], v[78:79], off offset:2048 nt
	global_load_dwordx4 v[8:11], v[78:79], off offset:3072 nt
	global_load_dwordx4 v[32:35], v[80:81], off offset:2048 nt
	global_load_dwordx4 v[12:15], v[80:81], off offset:3072 nt
	s_addc_u32 s21, s19, 0
	global_load_dwordx4 v[94:97], v90, s[20:21]
	global_load_dwordx4 v[98:101], v90, s[18:19]
	s_lshl_b64 s[8:9], s[8:9], 11
	s_lshl_b64 s[0:1], s[0:1], 11
	s_lshl_b64 s[4:5], s[4:5], 11
	v_lshl_add_u64 v[82:83], v[70:71], 0, s[8:9]
	v_lshl_add_u64 v[78:79], v[70:71], 0, s[0:1]
	v_lshl_add_u64 v[80:81], v[70:71], 0, s[4:5]
	s_lshl_b64 s[26:27], s[14:15], 11
	v_lshl_add_u64 v[76:77], v[70:71], 0, s[26:27]
	s_add_i32 s14, s14, s23
	global_load_dwordx4 v[164:167], v91, s[20:21]
	global_load_dwordx4 v[168:171], v[72:73], off offset:1024
	global_load_dwordx4 v[172:175], v90, s[18:19] offset:1024
	global_load_dwordx4 v[176:179], v92, s[20:21]
	global_load_dwordx4 v[180:183], v[72:73], off offset:2048
	global_load_dwordx4 v[184:187], v90, s[18:19] offset:2048
	global_load_dwordx4 v[188:191], v93, s[20:21]
	global_load_dwordx4 v[192:195], v[72:73], off offset:3072
	global_load_dwordx4 v[196:199], v90, s[18:19] offset:3072
	s_waitcnt vmcnt(22)
	v_pk_mul_f32 v[116:117], v[52:53], v[52:53]
	s_waitcnt vmcnt(21)
	v_pk_mul_f32 v[118:119], v[50:51], v[50:51]
	v_pk_mul_f32 v[102:103], v[38:39], v[38:39]
	v_pk_mul_f32 v[104:105], v[36:37], v[36:37]
	v_pk_mul_f32 v[106:107], v[22:23], v[22:23]
	v_pk_mul_f32 v[108:109], v[20:21], v[20:21]
	v_mul_f32_e32 v110, v17, v17
	v_mul_f32_e32 v112, v19, v19
	v_pk_mov_b32 v[114:115], v[104:105], v[102:103] op_sel:[1,0]
	v_mov_b32_e32 v105, v103
	v_pk_mov_b32 v[102:103], v[108:109], v[106:107] op_sel:[1,0]
	v_mov_b32_e32 v109, v107
	v_pk_mul_f32 v[106:107], v[54:55], v[54:55]
	v_pk_mul_f32 v[120:121], v[48:49], v[48:49]
	v_mul_f32_e32 v139, v2, v2
	v_mul_f32_e32 v141, v3, v3
	s_waitcnt vmcnt(20)
	v_pk_mul_f32 v[122:123], v[58:59], v[58:59]
	v_pk_mul_f32 v[124:125], v[56:57], v[56:57]
	s_waitcnt vmcnt(19)
	v_pk_mul_f32 v[126:127], v[46:47], v[46:47]
	v_pk_mul_f32 v[128:129], v[44:45], v[44:45]
	s_waitcnt vmcnt(18)
	v_pk_mul_f32 v[130:131], v[62:63], v[62:63]
	v_pk_mul_f32 v[132:133], v[60:61], v[60:61]
	s_waitcnt vmcnt(17)
	v_pk_mul_f32 v[134:135], v[42:43], v[42:43]
	v_pk_mul_f32 v[136:137], v[40:41], v[40:41]
	v_pk_fma_f32 v[110:111], v[16:17], v[16:17], v[110:111] op_sel_hi:[1,1,0]
	v_pk_fma_f32 v[112:113], v[18:19], v[18:19], v[112:113] op_sel_hi:[1,1,0]
	v_pk_add_f32 v[102:103], v[102:103], v[108:109]
	v_pk_mov_b32 v[108:109], v[116:117], v[106:107] op_sel:[1,0]
	v_mov_b32_e32 v117, v107
	v_pk_mov_b32 v[106:107], v[120:121], v[118:119] op_sel:[1,0]
	v_mov_b32_e32 v121, v119
	s_waitcnt vmcnt(16)
	v_mul_f32_e32 v140, v25, v25
	v_mul_f32_e32 v142, v27, v27
	v_pk_add_f32 v[104:105], v[114:115], v[104:105]
	v_pk_mov_b32 v[114:115], v[124:125], v[122:123] op_sel:[1,0]
	v_mov_b32_e32 v125, v123
	v_pk_mov_b32 v[118:119], v[128:129], v[126:127] op_sel:[1,0]
	v_mov_b32_e32 v129, v127
	v_pk_mov_b32 v[122:123], v[132:133], v[130:131] op_sel:[1,0]
	v_mov_b32_e32 v133, v131
	v_pk_mov_b32 v[126:127], v[136:137], v[134:135] op_sel:[1,0]
	v_mov_b32_e32 v137, v135
	v_mov_b32_e32 v111, v139
	v_mov_b32_e32 v113, v141
	v_pk_add_f32 v[108:109], v[108:109], v[116:117]
	v_pk_add_f32 v[106:107], v[106:107], v[120:121]
	v_mul_f32_e32 v149, v0, v0
	v_mul_f32_e32 v151, v1, v1
	s_waitcnt vmcnt(15)
	v_mul_f32_e32 v152, v6, v6
	v_mul_f32_e32 v153, v7, v7
	s_waitcnt vmcnt(14)
	v_mul_f32_e32 v144, v29, v29
	v_mul_f32_e32 v146, v31, v31
	s_waitcnt vmcnt(12)
	v_mul_f32_e32 v148, v33, v33
	v_mul_f32_e32 v150, v35, v35
	v_mul_f32_e32 v158, v4, v4
	v_mul_f32_e32 v159, v5, v5
	v_pk_fma_f32 v[130:131], v[24:25], v[24:25], v[140:141] op_sel_hi:[1,1,0]
	v_pk_fma_f32 v[134:135], v[26:27], v[26:27], v[142:143] op_sel_hi:[1,1,0]
	v_pk_add_f32 v[110:111], v[110:111], v[112:113]
	v_pk_add_f32 v[112:113], v[114:115], v[124:125]
	v_pk_add_f32 v[114:115], v[118:119], v[128:129]
	v_pk_add_f32 v[116:117], v[122:123], v[132:133]
	v_pk_add_f32 v[118:119], v[126:127], v[136:137]
	v_pk_add_f32 v[104:105], v[104:105], v[104:105] op_sel:[0,1] op_sel_hi:[1,0]
	v_pk_add_f32 v[102:103], v[102:103], v[102:103] op_sel:[0,1] op_sel_hi:[1,0]
	v_pk_add_f32 v[108:109], v[108:109], v[108:109] op_sel:[0,1] op_sel_hi:[1,0]
	v_pk_add_f32 v[106:107], v[106:107], v[106:107] op_sel:[0,1] op_sel_hi:[1,0]
	v_mul_f32_e32 v154, v10, v10
	v_mul_f32_e32 v155, v11, v11
	s_waitcnt vmcnt(11)
	v_mul_f32_e32 v156, v14, v14
	v_mul_f32_e32 v157, v15, v15
	v_mul_f32_e32 v160, v8, v8
	v_mul_f32_e32 v161, v9, v9
	v_mul_f32_e32 v162, v12, v12
	v_mul_f32_e32 v163, v13, v13
	v_pk_fma_f32 v[140:141], v[28:29], v[28:29], v[144:145] op_sel_hi:[1,1,0]
	v_pk_fma_f32 v[142:143], v[30:31], v[30:31], v[146:147] op_sel_hi:[1,1,0]
	v_pk_fma_f32 v[144:145], v[32:33], v[32:33], v[148:149] op_sel_hi:[1,1,0]
	v_pk_fma_f32 v[146:147], v[34:35], v[34:35], v[150:151] op_sel_hi:[1,1,0]
	v_mov_b32_e32 v131, v152
	v_mov_b32_e32 v135, v153
	v_mov_b32_e32 v105, v149
	v_mov_b32_e32 v103, v151
	v_pk_add_f32 v[112:113], v[112:113], v[112:113] op_sel:[0,1] op_sel_hi:[1,0]
	v_pk_add_f32 v[114:115], v[114:115], v[114:115] op_sel:[0,1] op_sel_hi:[1,0]
	v_pk_add_f32 v[116:117], v[116:117], v[116:117] op_sel:[0,1] op_sel_hi:[1,0]
	v_pk_add_f32 v[118:119], v[118:119], v[118:119] op_sel:[0,1] op_sel_hi:[1,0]
	s_waitcnt vmcnt(10)
	v_pk_add_f32 v[96:97], v[96:97], 1.0 op_sel_hi:[1,0]
	v_mov_b32_e32 v109, v158
	v_mov_b32_e32 v107, v159
	v_mov_b32_e32 v141, v154
	v_mov_b32_e32 v143, v155
	v_mov_b32_e32 v145, v156
	v_mov_b32_e32 v147, v157
	v_pk_add_f32 v[120:121], v[130:131], v[134:135]
	v_pk_add_f32 v[94:95], v[94:95], 1.0 op_sel_hi:[1,0]
	v_pk_add_f32 v[102:103], v[104:105], v[102:103]
	v_mov_b32_e32 v113, v160
	v_mov_b32_e32 v115, v161
	v_mov_b32_e32 v117, v162
	v_mov_b32_e32 v119, v163
	v_pk_mul_f32 v[66:67], v[66:67], v[96:97]
	v_pk_add_f32 v[96:97], v[108:109], v[106:107]
	v_pk_add_f32 v[122:123], v[140:141], v[142:143]
	v_pk_add_f32 v[124:125], v[144:145], v[146:147]
	v_pk_mul_f32 v[64:65], v[64:65], v[94:95]
	v_pk_add_f32 v[94:95], v[102:103], v[110:111]
	v_pk_add_f32 v[102:103], v[112:113], v[114:115]
	v_pk_add_f32 v[104:105], v[116:117], v[118:119]
	v_pk_add_f32 v[96:97], v[96:97], v[120:121]
	v_pk_add_f32 v[102:103], v[102:103], v[122:123]
	v_pk_add_f32 v[104:105], v[104:105], v[124:125]
	v_mov_b32_e32 v107, v94
	v_mov_b32_e32 v106, v96
	v_mov_b32_e32 v94, v97
	v_mov_b32_e32 v96, v104
	v_mov_b32_e32 v97, v102
	v_mov_b32_e32 v102, v105
	v_pk_add_f32 v[94:95], v[106:107], v[94:95]
	v_pk_add_f32 v[96:97], v[96:97], v[102:103]
	s_waitcnt lgkmcnt(2)
	s_waitcnt lgkmcnt(1)
	s_waitcnt lgkmcnt(2)
	s_waitcnt lgkmcnt(1)
	s_waitcnt lgkmcnt(2)
	s_waitcnt lgkmcnt(1)
	s_waitcnt lgkmcnt(2)
	s_waitcnt lgkmcnt(1)
	s_waitcnt lgkmcnt(2)
	s_waitcnt lgkmcnt(1)
	s_waitcnt lgkmcnt(2)
	s_nop 1
	v_add_f32_dpp v94, v94, v94 row_ror:8 row_mask:0xf bank_mask:0xf
	v_add_f32_dpp v95, v95, v95 row_ror:8 row_mask:0xf bank_mask:0xf
	s_nop 0
	v_add_f32_dpp v94, v94, v94 row_ror:4 row_mask:0xf bank_mask:0xf
	v_add_f32_dpp v95, v95, v95 row_ror:4 row_mask:0xf bank_mask:0xf
	s_nop 0
	v_add_f32_dpp v94, v94, v94 row_ror:2 row_mask:0xf bank_mask:0xf
	v_add_f32_dpp v95, v95, v95 row_ror:2 row_mask:0xf bank_mask:0xf
	s_nop 0
	v_add_f32_dpp v94, v94, v94 row_ror:1 row_mask:0xf bank_mask:0xf
	v_add_f32_dpp v95, v95, v95 row_ror:1 row_mask:0xf bank_mask:0xf
	v_mov_b32_e32 v102, v94
	v_mov_b32_e32 v103, v95
	s_nop 1
	v_permlane16_swap_b32 v94, v102
	v_permlane16_swap_b32 v95, v103
	s_nop 1
	v_add_f32_e32 v94, v94, v102
	v_add_f32_e32 v95, v95, v103
	v_mov_b32_e32 v102, v94
	v_mov_b32_e32 v103, v95
	s_nop 1
	v_permlane32_swap_b32 v94, v102
	v_permlane32_swap_b32 v95, v103
	s_nop 1
	v_pk_add_f32 v[94:95], v[94:95], v[102:103]
	s_nop 0
	v_pk_fma_f32 v[94:95], v[94:95], s[16:17], v[74:75] op_sel_hi:[1,0,0]
	s_waitcnt lgkmcnt(0)
	s_nop 1
	v_add_f32_dpp v96, v96, v96 row_ror:8 row_mask:0xf bank_mask:0xf
	v_add_f32_dpp v97, v97, v97 row_ror:8 row_mask:0xf bank_mask:0xf
	s_nop 0
	v_add_f32_dpp v96, v96, v96 row_ror:4 row_mask:0xf bank_mask:0xf
	v_add_f32_dpp v97, v97, v97 row_ror:4 row_mask:0xf bank_mask:0xf
	s_nop 0
	v_add_f32_dpp v96, v96, v96 row_ror:2 row_mask:0xf bank_mask:0xf
	v_add_f32_dpp v97, v97, v97 row_ror:2 row_mask:0xf bank_mask:0xf
	s_nop 0
	v_add_f32_dpp v96, v96, v96 row_ror:1 row_mask:0xf bank_mask:0xf
	v_add_f32_dpp v97, v97, v97 row_ror:1 row_mask:0xf bank_mask:0xf
	v_mov_b32_e32 v104, v96
	v_mov_b32_e32 v105, v97
	s_nop 1
	v_permlane16_swap_b32 v96, v104
	v_permlane16_swap_b32 v97, v105
	s_nop 1
	v_add_f32_e32 v96, v96, v104
	v_add_f32_e32 v97, v97, v105
	v_mov_b32_e32 v104, v96
	v_mov_b32_e32 v105, v97
	s_nop 1
	v_permlane32_swap_b32 v96, v104
	v_permlane32_swap_b32 v97, v105
	s_nop 1
	v_pk_add_f32 v[96:97], v[96:97], v[104:105]
	v_mul_f32_e32 v103, 0x4b800000, v95
	v_pk_fma_f32 v[96:97], v[96:97], s[16:17], v[74:75] op_sel_hi:[1,0,0]
	v_cmp_gt_f32_e64 s[8:9], s24, v95
	v_mul_f32_e32 v102, 0x4b800000, v94
	v_cmp_gt_f32_e32 vcc, s24, v94
	v_mul_f32_e32 v104, 0x4b800000, v96
	v_cmp_gt_f32_e64 s[0:1], s24, v96
	v_mul_f32_e32 v105, 0x4b800000, v97
	v_cmp_gt_f32_e64 s[4:5], s24, v97
	v_cndmask_b32_e64 v95, v95, v103, s[8:9]
	v_cndmask_b32_e32 v94, v94, v102, vcc
	v_cndmask_b32_e64 v97, v97, v105, s[4:5]
	v_cndmask_b32_e64 v96, v96, v104, s[0:1]
	v_rsq_f32_e32 v95, v95
	v_rsq_f32_e32 v102, v94
	v_rsq_f32_e32 v97, v97
	v_rsq_f32_e32 v103, v96
	v_mul_f32_e32 v94, 0x45800000, v95
	v_mul_f32_e32 v96, 0x45800000, v102
	v_mul_f32_e32 v104, 0x45800000, v97
	v_mul_f32_e32 v105, 0x45800000, v103
	v_cndmask_b32_e64 v94, v95, v94, s[8:9]
	v_cndmask_b32_e32 v96, v102, v96, vcc
	v_cndmask_b32_e64 v102, v97, v104, s[4:5]
	v_cndmask_b32_e64 v104, v103, v105, s[0:1]
	v_pk_mul_f32 v[36:37], v[36:37], v[94:95] op_sel_hi:[1,0]
	v_pk_mul_f32 v[38:39], v[38:39], v[94:95] op_sel_hi:[1,0]
	v_pk_mul_f32 v[52:53], v[52:53], v[96:97] op_sel_hi:[1,0]
	v_pk_mul_f32 v[54:55], v[54:55], v[96:97] op_sel_hi:[1,0]
	v_pk_mul_f32 v[56:57], v[56:57], v[102:103] op_sel_hi:[1,0]
	v_pk_mul_f32 v[58:59], v[58:59], v[102:103] op_sel_hi:[1,0]
	v_pk_mul_f32 v[60:61], v[60:61], v[104:105] op_sel_hi:[1,0]
	v_pk_mul_f32 v[62:63], v[62:63], v[104:105] op_sel_hi:[1,0]
	s_waitcnt vmcnt(0)
	v_pk_fma_f32 v[38:39], v[38:39], v[66:67], v[100:101]
	v_pk_fma_f32 v[36:37], v[36:37], v[64:65], v[98:99]
	v_pk_fma_f32 v[54:55], v[54:55], v[66:67], v[100:101]
	v_pk_fma_f32 v[58:59], v[66:67], v[58:59], v[100:101]
	v_pk_fma_f32 v[62:63], v[66:67], v[62:63], v[100:101]
	v_pk_fma_f32 v[52:53], v[52:53], v[64:65], v[98:99]
	v_pk_fma_f32 v[56:57], v[64:65], v[56:57], v[98:99]
	v_pk_fma_f32 v[60:61], v[64:65], v[60:61], v[98:99]
	v_cvt_pk_bf16_f32 v36, v36, v37
	v_cvt_pk_bf16_f32 v37, v38, v39
	v_cvt_pk_bf16_f32 v38, v52, v53
	v_cvt_pk_bf16_f32 v39, v54, v55
	v_cvt_pk_bf16_f32 v52, v56, v57
	v_cvt_pk_bf16_f32 v53, v58, v59
	v_cvt_pk_bf16_f32 v54, v60, v61
	v_cvt_pk_bf16_f32 v55, v62, v63
	global_store_dwordx2 v[76:77], v[36:37], off
	global_store_dwordx2 v[78:79], v[38:39], off
	global_store_dwordx2 v[80:81], v[52:53], off
	global_store_dwordx2 v[82:83], v[54:55], off
	s_nop 0
	v_pk_mul_f32 v[20:21], v[20:21], v[94:95] op_sel_hi:[1,0]
	v_pk_mul_f32 v[22:23], v[22:23], v[94:95] op_sel_hi:[1,0]
	v_pk_mul_f32 v[48:49], v[48:49], v[96:97] op_sel_hi:[1,0]
	v_pk_mul_f32 v[50:51], v[50:51], v[96:97] op_sel_hi:[1,0]
	v_pk_mul_f32 v[44:45], v[44:45], v[102:103] op_sel_hi:[1,0]
	v_pk_mul_f32 v[46:47], v[46:47], v[102:103] op_sel_hi:[1,0]
	v_pk_mul_f32 v[40:41], v[40:41], v[104:105] op_sel_hi:[1,0]
	v_pk_mul_f32 v[42:43], v[42:43], v[104:105] op_sel_hi:[1,0]
	v_pk_mul_f32 v[16:17], v[16:17], v[94:95] op_sel_hi:[1,0]
	v_pk_mul_f32 v[18:19], v[18:19], v[94:95] op_sel_hi:[1,0]
	v_pk_mul_f32 v[24:25], v[24:25], v[96:97] op_sel_hi:[1,0]
	v_pk_mul_f32 v[26:27], v[26:27], v[96:97] op_sel_hi:[1,0]
	v_pk_mul_f32 v[28:29], v[28:29], v[102:103] op_sel_hi:[1,0]
	v_pk_mul_f32 v[30:31], v[30:31], v[102:103] op_sel_hi:[1,0]
	v_pk_mul_f32 v[32:33], v[32:33], v[104:105] op_sel_hi:[1,0]
	v_pk_mul_f32 v[34:35], v[34:35], v[104:105] op_sel_hi:[1,0]
	v_pk_mul_f32 v[0:1], v[0:1], v[94:95] op_sel_hi:[1,0]
	v_pk_mul_f32 v[2:3], v[2:3], v[94:95] op_sel_hi:[1,0]
	s_add_i32 s17, s17, s22
	v_pk_mul_f32 v[4:5], v[4:5], v[96:97] op_sel_hi:[1,0]
	v_pk_mul_f32 v[6:7], v[6:7], v[96:97] op_sel_hi:[1,0]
	v_pk_mul_f32 v[8:9], v[8:9], v[102:103] op_sel_hi:[1,0]
	v_pk_mul_f32 v[10:11], v[10:11], v[102:103] op_sel_hi:[1,0]
	v_pk_mul_f32 v[12:13], v[12:13], v[104:105] op_sel_hi:[1,0]
	v_pk_mul_f32 v[14:15], v[14:15], v[104:105] op_sel_hi:[1,0]
	s_cmpk_lt_i32 s17, 0x4000
	v_pk_add_f32 v[38:39], v[166:167], 1.0 op_sel_hi:[1,0]
	v_pk_add_f32 v[36:37], v[164:165], 1.0 op_sel_hi:[1,0]
	v_pk_mul_f32 v[38:39], v[170:171], v[38:39]
	v_pk_mul_f32 v[36:37], v[168:169], v[36:37]
	v_pk_fma_f32 v[22:23], v[22:23], v[38:39], v[174:175]
	v_pk_fma_f32 v[20:21], v[20:21], v[36:37], v[172:173]
	v_pk_fma_f32 v[50:51], v[50:51], v[38:39], v[174:175]
	v_pk_fma_f32 v[48:49], v[48:49], v[36:37], v[172:173]
	v_pk_fma_f32 v[46:47], v[46:47], v[38:39], v[174:175]
	v_pk_fma_f32 v[44:45], v[44:45], v[36:37], v[172:173]
	v_pk_fma_f32 v[38:39], v[38:39], v[42:43], v[174:175]
	v_pk_fma_f32 v[36:37], v[36:37], v[40:41], v[172:173]
	v_cvt_pk_bf16_f32 v20, v20, v21
	v_cvt_pk_bf16_f32 v21, v22, v23
	v_cvt_pk_bf16_f32 v22, v48, v49
	v_cvt_pk_bf16_f32 v23, v50, v51
	v_cvt_pk_bf16_f32 v40, v44, v45
	v_cvt_pk_bf16_f32 v41, v46, v47
	v_cvt_pk_bf16_f32 v36, v36, v37
	v_cvt_pk_bf16_f32 v37, v38, v39
	global_store_dwordx2 v[76:77], v[20:21], off offset:512
	global_store_dwordx2 v[78:79], v[22:23], off offset:512
	global_store_dwordx2 v[80:81], v[40:41], off offset:512
	global_store_dwordx2 v[82:83], v[36:37], off offset:512
	s_nop 0
	v_pk_add_f32 v[22:23], v[178:179], 1.0 op_sel_hi:[1,0]
	v_pk_add_f32 v[20:21], v[176:177], 1.0 op_sel_hi:[1,0]
	v_pk_mul_f32 v[22:23], v[182:183], v[22:23]
	v_pk_mul_f32 v[20:21], v[180:181], v[20:21]
	v_pk_fma_f32 v[18:19], v[18:19], v[22:23], v[186:187]
	v_pk_fma_f32 v[16:17], v[16:17], v[20:21], v[184:185]
	v_pk_fma_f32 v[26:27], v[26:27], v[22:23], v[186:187]
	v_pk_fma_f32 v[24:25], v[24:25], v[20:21], v[184:185]
	v_pk_fma_f32 v[30:31], v[30:31], v[22:23], v[186:187]
	v_pk_fma_f32 v[28:29], v[28:29], v[20:21], v[184:185]
	v_pk_fma_f32 v[22:23], v[34:35], v[22:23], v[186:187]
	v_pk_fma_f32 v[20:21], v[32:33], v[20:21], v[184:185]
	v_cvt_pk_bf16_f32 v16, v16, v17
	v_cvt_pk_bf16_f32 v17, v18, v19
	v_cvt_pk_bf16_f32 v18, v24, v25
	v_cvt_pk_bf16_f32 v19, v26, v27
	v_cvt_pk_bf16_f32 v24, v28, v29
	v_cvt_pk_bf16_f32 v25, v30, v31
	v_cvt_pk_bf16_f32 v20, v20, v21
	v_cvt_pk_bf16_f32 v21, v22, v23
	global_store_dwordx2 v[76:77], v[16:17], off offset:1024
	global_store_dwordx2 v[78:79], v[18:19], off offset:1024
	global_store_dwordx2 v[80:81], v[24:25], off offset:1024
	global_store_dwordx2 v[82:83], v[20:21], off offset:1024
	s_nop 0
	v_pk_add_f32 v[18:19], v[190:191], 1.0 op_sel_hi:[1,0]
	v_pk_add_f32 v[16:17], v[188:189], 1.0 op_sel_hi:[1,0]
	v_pk_mul_f32 v[18:19], v[194:195], v[18:19]
	v_pk_mul_f32 v[16:17], v[192:193], v[16:17]
	v_pk_fma_f32 v[2:3], v[2:3], v[18:19], v[198:199]
	v_pk_fma_f32 v[0:1], v[0:1], v[16:17], v[196:197]
	v_pk_fma_f32 v[6:7], v[6:7], v[18:19], v[198:199]
	v_pk_fma_f32 v[4:5], v[4:5], v[16:17], v[196:197]
	v_pk_fma_f32 v[10:11], v[10:11], v[18:19], v[198:199]
	v_pk_fma_f32 v[8:9], v[8:9], v[16:17], v[196:197]
	v_pk_fma_f32 v[14:15], v[14:15], v[18:19], v[198:199]
	v_pk_fma_f32 v[12:13], v[12:13], v[16:17], v[196:197]
	v_cvt_pk_bf16_f32 v0, v0, v1
	v_cvt_pk_bf16_f32 v1, v2, v3
	v_cvt_pk_bf16_f32 v2, v4, v5
	v_cvt_pk_bf16_f32 v3, v6, v7
	v_cvt_pk_bf16_f32 v4, v8, v9
	v_cvt_pk_bf16_f32 v5, v10, v11
	v_cvt_pk_bf16_f32 v6, v12, v13
	v_cvt_pk_bf16_f32 v7, v14, v15
	global_store_dwordx2 v[76:77], v[0:1], off offset:1536
	global_store_dwordx2 v[78:79], v[2:3], off offset:1536
	global_store_dwordx2 v[80:81], v[4:5], off offset:1536
	global_store_dwordx2 v[82:83], v[6:7], off offset:1536
	s_cbranch_scc1 .LBB0_113

.LBB0_316:
	s_ashr_i32 s18, s9, 12
	s_ashr_i32 s5, s4, 31
	s_add_i32 s0, s4, 1
	s_mul_i32 s18, s18, 9
	s_lshl_b64 s[14:15], s[4:5], 11
	s_lshl_b64 s[16:17], s[4:5], 12
	s_ashr_i32 s1, s0, 31
	s_ashr_i32 s19, s18, 31
	v_lshl_add_u64 v[4:5], v[40:41], 0, s[14:15]
	v_lshl_add_u64 v[6:7], v[42:43], 0, s[16:17]
	s_lshl_b64 s[16:17], s[0:1], 12
	v_lshl_add_u64 v[66:67], v[44:45], 0, s[14:15]
	s_lshl_b64 s[14:15], s[18:19], 12
	s_add_u32 s5, s2, s14
	s_addc_u32 s19, s3, s15
	s_add_u32 s14, s5, 0x2000
	global_load_dwordx4 v[32:35], v[48:49], off
	global_load_dwordx2 v[86:87], v[4:5], off
	global_load_dwordx2 v[84:85], v[4:5], off offset:512
	global_load_dwordx2 v[82:83], v[4:5], off offset:1024
	global_load_dwordx2 v[80:81], v[4:5], off offset:1536
	global_load_dwordx2 v[78:79], v[4:5], off offset:2048
	global_load_dwordx2 v[76:77], v[4:5], off offset:2560
	global_load_dwordx2 v[74:75], v[4:5], off offset:3072
	global_load_dwordx2 v[72:73], v[4:5], off offset:3584
	global_load_dwordx4 v[24:27], v[6:7], off nt
	global_load_dwordx4 v[16:19], v[6:7], off offset:1024 nt
	global_load_dwordx4 v[8:11], v[6:7], off offset:2048 nt
	global_load_dwordx4 v[0:3], v[6:7], off offset:3072 nt
	v_lshl_add_u64 v[36:37], v[42:43], 0, s[16:17]
	s_addc_u32 s15, s19, 0
	global_load_dwordx4 v[28:31], v[36:37], off nt
	global_load_dwordx4 v[20:23], v[36:37], off offset:1024 nt
	global_load_dwordx4 v[12:15], v[36:37], off offset:2048 nt
	global_load_dwordx4 v[4:7], v[36:37], off offset:3072 nt
	s_lshl_b64 s[0:1], s[0:1], 11
	global_load_dwordx4 v[36:39], v94, s[14:15]
	s_add_u32 s16, s5, 0x3000
	s_addc_u32 s17, s19, 0
	s_add_u32 s18, s5, 0x4000
	v_lshl_add_u64 v[68:69], v[44:45], 0, s[0:1]
	s_addc_u32 s19, s19, 0
	s_and_b32 s0, s21, 0x8000
	s_and_b32 s1, s9, 0xfffff000
	s_and_b32 s5, s4, 0xffe
	s_add_i32 s0, s0, s1
	s_or_b32 s0, s0, s5
	s_ashr_i32 s1, s0, 31
	s_lshl_b64 s[0:1], s[0:1], 11
	v_lshl_add_u64 v[70:71], v[46:47], 0, s[0:1]
	s_add_i32 s21, s21, s22
	s_add_i32 s4, s4, s23
	global_load_dwordx4 v[152:155], v95, s[14:15]
	global_load_dwordx4 v[156:159], v[50:51], off
	global_load_dwordx4 v[160:163], v96, s[14:15]
	global_load_dwordx4 v[164:167], v[52:53], off
	global_load_dwordx4 v[168:171], v97, s[14:15]
	global_load_dwordx4 v[172:175], v[54:55], off
	global_load_dwordx4 v[176:179], v94, s[18:19]
	global_load_dwordx4 v[180:183], v[56:57], off
	global_load_dwordx4 v[184:187], v94, s[16:17]
	global_load_dwordx4 v[188:191], v95, s[18:19]
	global_load_dwordx4 v[192:195], v[58:59], off
	global_load_dwordx4 v[196:199], v95, s[16:17]
	global_load_dwordx4 v[200:203], v96, s[18:19]
	global_load_dwordx4 v[204:207], v[60:61], off
	global_load_dwordx4 v[220:223], v96, s[16:17]
	global_load_dwordx4 v[224:227], v97, s[18:19]
	global_load_dwordx4 v[228:231], v[62:63], off
	global_load_dwordx4 v[232:235], v97, s[16:17]
	s_waitcnt vmcnt(34)
	v_lshlrev_b32_e32 v98, 16, v86
	v_and_b32_e32 v99, 0xffff0000, v86
	v_lshlrev_b32_e32 v86, 16, v87
	v_and_b32_e32 v87, 0xffff0000, v87
	s_waitcnt vmcnt(33)
	v_lshlrev_b32_e32 v101, 16, v85
	v_lshlrev_b32_e32 v100, 16, v84
	v_and_b32_e32 v85, 0xffff0000, v85
	v_and_b32_e32 v84, 0xffff0000, v84
	s_waitcnt vmcnt(30)
	v_lshlrev_b32_e32 v108, 16, v78
	v_and_b32_e32 v109, 0xffff0000, v78
	v_lshlrev_b32_e32 v78, 16, v79
	v_and_b32_e32 v79, 0xffff0000, v79
	s_waitcnt vmcnt(29)
	v_lshlrev_b32_e32 v111, 16, v77
	v_lshlrev_b32_e32 v110, 16, v76
	v_and_b32_e32 v77, 0xffff0000, v77
	v_and_b32_e32 v76, 0xffff0000, v76
	v_lshlrev_b32_e32 v102, 16, v82
	v_and_b32_e32 v103, 0xffff0000, v82
	v_lshlrev_b32_e32 v82, 16, v83
	v_and_b32_e32 v83, 0xffff0000, v83
	v_lshlrev_b32_e32 v105, 16, v80
	s_waitcnt vmcnt(27)
	v_lshlrev_b32_e32 v115, 16, v72
	v_mul_f32_e32 v104, v87, v87
	v_pk_mul_f32 v[118:119], v[84:85], v[84:85]
	v_mul_f32_e32 v114, v99, v99
	v_mul_f32_e32 v124, v79, v79
	v_pk_mul_f32 v[126:127], v[76:77], v[76:77]
	v_mul_f32_e32 v128, v109, v109
	v_and_b32_e32 v107, 0xffff0000, v80
	v_lshlrev_b32_e32 v112, 16, v74
	v_and_b32_e32 v113, 0xffff0000, v74
	v_lshlrev_b32_e32 v74, 16, v75
	v_and_b32_e32 v75, 0xffff0000, v75
	v_mov_b32_e32 v121, v105
	v_mul_f32_e32 v120, v103, v103
	v_mul_f32_e32 v122, v83, v83
	v_mov_b32_e32 v123, v115
	v_mov_b32_e32 v134, v100
	v_mov_b32_e32 v135, v84
	v_mov_b32_e32 v84, v101
	v_mov_b32_e32 v136, v110
	v_mov_b32_e32 v137, v76
	v_mov_b32_e32 v76, v111
	v_pk_fma_f32 v[140:141], v[86:87], v[86:87], v[104:105] op_sel_hi:[1,1,0]
	v_pk_fma_f32 v[100:101], v[100:101], v[100:101], v[118:119]
	v_pk_fma_f32 v[118:119], v[98:99], v[98:99], v[114:115] op_sel_hi:[1,1,0]
	v_pk_fma_f32 v[124:125], v[78:79], v[78:79], v[124:125] op_sel_hi:[1,1,0]
	v_pk_fma_f32 v[110:111], v[110:111], v[110:111], v[126:127]
	v_pk_fma_f32 v[126:127], v[108:109], v[108:109], v[128:129] op_sel_hi:[1,1,0]
	v_lshlrev_b32_e32 v80, 16, v81
	v_and_b32_e32 v81, 0xffff0000, v81
	v_and_b32_e32 v117, 0xffff0000, v72
	v_lshlrev_b32_e32 v72, 16, v73
	v_and_b32_e32 v73, 0xffff0000, v73
	v_mul_f32_e32 v133, v107, v107
	v_mul_f32_e32 v130, v113, v113
	v_mul_f32_e32 v132, v75, v75
	v_pk_fma_f32 v[142:143], v[102:103], v[102:103], v[120:121] op_sel_hi:[1,1,0]
	v_pk_fma_f32 v[144:145], v[82:83], v[82:83], v[122:123] op_sel_hi:[1,1,0]
	v_mov_b32_e32 v104, v118
	v_mov_b32_e32 v120, v140
	v_mov_b32_e32 v114, v126
	v_mov_b32_e32 v122, v124
	v_mul_f32_e32 v139, v80, v80
	v_mul_f32_e32 v146, v81, v81
	v_mul_f32_e32 v147, v117, v117
	v_mul_f32_e32 v148, v72, v72
	v_mul_f32_e32 v149, v73, v73
	v_mov_b32_e32 v106, v105
	v_mov_b32_e32 v116, v115
	v_pk_fma_f32 v[128:129], v[112:113], v[112:113], v[130:131] op_sel_hi:[1,1,0]
	v_pk_fma_f32 v[130:131], v[74:75], v[74:75], v[132:133] op_sel_hi:[1,1,0]
	v_pk_add_f32 v[118:119], v[118:119], v[140:141]
	v_pk_add_f32 v[100:101], v[100:101], v[100:101] op_sel:[0,1] op_sel_hi:[1,0]
	v_pk_add_f32 v[124:125], v[126:127], v[124:125]
	v_pk_add_f32 v[110:111], v[110:111], v[110:111] op_sel:[0,1] op_sel_hi:[1,0]
	v_pk_mul_f32 v[104:105], v[104:105], v[120:121]
	v_pk_mul_f32 v[114:115], v[114:115], v[122:123]
	v_mov_b32_e32 v143, v139
	v_mov_b32_e32 v145, v146
	v_mov_b32_e32 v129, v148
	v_mov_b32_e32 v131, v149
	v_mov_b32_e32 v101, v133
	v_mov_b32_e32 v111, v147
	v_mov_b32_e32 v119, v105
	v_mov_b32_e32 v125, v115
	v_pk_add_f32 v[120:121], v[142:143], v[144:145]
	v_pk_add_f32 v[122:123], v[128:129], v[130:131]
	s_waitcnt vmcnt(0)
	v_pk_mul_f32 v[34:35], v[38:39], v[34:35]
	v_pk_mul_f32 v[32:33], v[36:37], v[32:33]
	v_pk_add_f32 v[36:37], v[118:119], v[100:101]
	v_pk_add_f32 v[38:39], v[124:125], v[110:111]
	v_pk_add_f32 v[36:37], v[36:37], v[120:121]
	v_pk_add_f32 v[38:39], v[38:39], v[122:123]
	v_mov_b32_e32 v101, v36
	v_mov_b32_e32 v100, v38
	v_mov_b32_e32 v36, v39
	v_pk_add_f32 v[36:37], v[100:101], v[36:37]
	s_waitcnt lgkmcnt(0)
	s_waitcnt lgkmcnt(0)
	s_waitcnt lgkmcnt(0)
	s_waitcnt lgkmcnt(0)
	s_waitcnt lgkmcnt(0)
	s_waitcnt lgkmcnt(0)
	s_nop 1
	v_add_f32_dpp v36, v36, v36 row_ror:8 row_mask:0xf bank_mask:0xf
	v_add_f32_dpp v37, v37, v37 row_ror:8 row_mask:0xf bank_mask:0xf
	s_nop 0
	v_add_f32_dpp v36, v36, v36 row_ror:4 row_mask:0xf bank_mask:0xf
	v_add_f32_dpp v37, v37, v37 row_ror:4 row_mask:0xf bank_mask:0xf
	s_nop 0
	v_add_f32_dpp v36, v36, v36 row_ror:2 row_mask:0xf bank_mask:0xf
	v_add_f32_dpp v37, v37, v37 row_ror:2 row_mask:0xf bank_mask:0xf
	s_nop 0
	v_add_f32_dpp v36, v36, v36 row_ror:1 row_mask:0xf bank_mask:0xf
	v_add_f32_dpp v37, v37, v37 row_ror:1 row_mask:0xf bank_mask:0xf
	v_mov_b32_e32 v38, v36
	v_mov_b32_e32 v39, v37
	s_nop 1
	v_permlane16_swap_b32 v36, v38
	v_permlane16_swap_b32 v37, v39
	s_nop 1
	v_add_f32_e32 v36, v36, v38
	v_add_f32_e32 v37, v37, v39
	v_mov_b32_e32 v38, v36
	v_mov_b32_e32 v39, v37
	s_nop 1
	v_permlane32_swap_b32 v36, v38
	v_permlane32_swap_b32 v37, v39
	s_nop 1
	v_pk_add_f32 v[36:37], v[36:37], v[38:39]
	s_nop 0
	v_pk_fma_f32 v[36:37], v[36:37], s[8:9], v[64:65] op_sel_hi:[1,0,0]
	s_nop 0
	v_mul_f32_e32 v38, 0x4b800000, v37
	v_cmp_gt_f32_e64 s[0:1], s24, v37
	v_mul_f32_e32 v39, 0x4b800000, v36
	v_cmp_gt_f32_e32 vcc, s24, v36
	v_cndmask_b32_e64 v37, v37, v38, s[0:1]
	v_rsq_f32_e32 v37, v37
	v_cndmask_b32_e32 v36, v36, v39, vcc
	v_rsq_f32_e32 v36, v36
	v_mul_f32_e32 v38, 0x45800000, v37
	v_cndmask_b32_e64 v37, v37, v38, s[0:1]
	v_mul_f32_e32 v39, 0x45800000, v36
	v_cndmask_b32_e32 v38, v36, v39, vcc
	v_mul_f32_e32 v36, 0.5, v37
	v_mul_f32_e32 v38, 0.5, v38
	v_pk_mul_f32 v[98:99], v[36:37], v[98:99] op_sel_hi:[0,1]
	v_pk_mul_f32 v[86:87], v[36:37], v[86:87] op_sel_hi:[0,1]
	v_pk_mul_f32 v[100:101], v[38:39], v[108:109] op_sel_hi:[0,1]
	v_pk_mul_f32 v[78:79], v[38:39], v[78:79] op_sel_hi:[0,1]
	v_pk_mul_f32 v[104:105], v[36:37], v[134:135] op_sel_hi:[0,1]
	v_pk_mul_f32 v[84:85], v[36:37], v[84:85] op_sel_hi:[0,1]
	v_pk_mul_f32 v[108:109], v[38:39], v[136:137] op_sel_hi:[0,1]
	v_pk_mul_f32 v[76:77], v[38:39], v[76:77] op_sel_hi:[0,1]
	v_pk_mul_f32 v[102:103], v[36:37], v[102:103] op_sel_hi:[0,1]
	v_pk_mul_f32 v[82:83], v[36:37], v[82:83] op_sel_hi:[0,1]
	v_pk_mul_f32 v[110:111], v[38:39], v[112:113] op_sel_hi:[0,1]
	v_pk_mul_f32 v[74:75], v[38:39], v[74:75] op_sel_hi:[0,1]
	v_pk_mul_f32 v[106:107], v[36:37], v[106:107] op_sel_hi:[0,1]
	v_pk_mul_f32 v[36:37], v[36:37], v[80:81] op_sel_hi:[0,1]
	v_pk_mul_f32 v[80:81], v[38:39], v[116:117] op_sel_hi:[0,1]
	v_pk_mul_f32 v[38:39], v[38:39], v[72:73] op_sel_hi:[0,1]
	v_pk_fma_f32 v[72:73], v[34:35], v[86:87], v[26:27]
	v_pk_fma_f32 v[86:87], v[32:33], v[98:99], v[24:25]
	v_pk_fma_f32 v[34:35], v[34:35], v[78:79], v[30:31]
	v_pk_fma_f32 v[32:33], v[32:33], v[100:101], v[28:29]
	v_cvt_pk_bf16_f32 v24, v86, v87
	v_cvt_pk_bf16_f32 v25, v72, v73
	v_cvt_pk_bf16_f32 v26, v32, v33
	v_cvt_pk_bf16_f32 v27, v34, v35
	global_store_dwordx2 v[66:67], v[24:25], off
	global_store_dwordx2 v[68:69], v[26:27], off
	s_nop 0
	v_pk_mul_f32 v[78:79], v[72:73], v[72:73]
	v_pk_mul_f32 v[98:99], v[86:87], v[86:87]
	v_pk_mul_f32 v[100:101], v[34:35], v[34:35]
	v_pk_mul_f32 v[26:27], v[154:155], v[158:159]
	v_pk_mul_f32 v[24:25], v[152:153], v[156:157]
	v_pk_fma_f32 v[28:29], v[26:27], v[84:85], v[18:19]
	v_pk_fma_f32 v[30:31], v[24:25], v[104:105], v[16:17]
	v_pk_fma_f32 v[26:27], v[26:27], v[76:77], v[22:23]
	v_pk_fma_f32 v[24:25], v[24:25], v[108:109], v[20:21]
	v_cvt_pk_bf16_f32 v16, v30, v31
	v_cvt_pk_bf16_f32 v17, v28, v29
	v_cvt_pk_bf16_f32 v18, v24, v25
	v_cvt_pk_bf16_f32 v19, v26, v27
	global_store_dwordx2 v[66:67], v[16:17], off offset:512
	global_store_dwordx2 v[68:69], v[18:19], off offset:512
	s_nop 0
	v_pk_mul_f32 v[76:77], v[32:33], v[32:33]
	v_pk_mov_b32 v[84:85], v[98:99], v[78:79] op_sel:[1,0]
	v_mov_b32_e32 v99, v79
	v_pk_mov_b32 v[78:79], v[76:77], v[100:101] op_sel:[1,0]
	v_mov_b32_e32 v77, v101
	v_pk_add_f32 v[84:85], v[84:85], v[98:99]
	v_pk_add_f32 v[76:77], v[78:79], v[76:77]
	v_pk_add_f32 v[78:79], v[84:85], v[84:85] op_sel:[0,1] op_sel_hi:[1,0]
	v_pk_mul_f32 v[84:85], v[30:31], v[30:31]
	v_pk_mul_f32 v[98:99], v[26:27], v[26:27]
	v_pk_add_f32 v[76:77], v[76:77], v[76:77] op_sel:[0,1] op_sel_hi:[1,0]
	v_pk_mul_f32 v[18:19], v[162:163], v[166:167]
	v_pk_mul_f32 v[16:17], v[160:161], v[164:165]
	v_pk_fma_f32 v[20:21], v[82:83], v[18:19], v[10:11]
	v_pk_fma_f32 v[22:23], v[102:103], v[16:17], v[8:9]
	v_pk_fma_f32 v[18:19], v[18:19], v[74:75], v[14:15]
	v_pk_fma_f32 v[16:17], v[16:17], v[110:111], v[12:13]
	v_cvt_pk_bf16_f32 v8, v22, v23
	v_cvt_pk_bf16_f32 v9, v20, v21
	v_cvt_pk_bf16_f32 v10, v16, v17
	v_cvt_pk_bf16_f32 v11, v18, v19
	global_store_dwordx2 v[66:67], v[8:9], off offset:1024
	global_store_dwordx2 v[68:69], v[10:11], off offset:1024
	s_nop 0
	v_pk_mul_f32 v[74:75], v[28:29], v[28:29]
	v_pk_mul_f32 v[82:83], v[24:25], v[24:25]
	v_pk_mov_b32 v[100:101], v[84:85], v[74:75] op_sel:[1,0]
	v_mov_b32_e32 v85, v75
	v_pk_mov_b32 v[74:75], v[82:83], v[98:99] op_sel:[1,0]
	v_mov_b32_e32 v83, v99
	v_pk_add_f32 v[84:85], v[100:101], v[84:85]
	v_pk_add_f32 v[74:75], v[74:75], v[82:83]
	v_pk_add_f32 v[82:83], v[84:85], v[84:85] op_sel:[0,1] op_sel_hi:[1,0]
	v_mul_f32_e32 v84, v23, v23
	v_mul_f32_e32 v98, v21, v21
	v_mul_f32_e32 v100, v17, v17
	v_mul_f32_e32 v102, v19, v19
	v_pk_add_f32 v[74:75], v[74:75], v[74:75] op_sel:[0,1] op_sel_hi:[1,0]
	v_pk_fma_f32 v[84:85], v[22:23], v[22:23], v[84:85] op_sel_hi:[1,1,0]
	v_pk_fma_f32 v[98:99], v[20:21], v[20:21], v[98:99] op_sel_hi:[1,1,0]
	v_pk_fma_f32 v[100:101], v[16:17], v[16:17], v[100:101] op_sel_hi:[1,1,0]
	v_pk_fma_f32 v[102:103], v[18:19], v[18:19], v[102:103] op_sel_hi:[1,1,0]
	v_pk_mul_f32 v[10:11], v[170:171], v[174:175]
	v_pk_mul_f32 v[8:9], v[168:169], v[172:173]
	v_pk_fma_f32 v[12:13], v[36:37], v[10:11], v[2:3]
	v_pk_fma_f32 v[14:15], v[106:107], v[8:9], v[0:1]
	v_pk_fma_f32 v[36:37], v[38:39], v[10:11], v[6:7]
	v_pk_fma_f32 v[38:39], v[80:81], v[8:9], v[4:5]
	v_cvt_pk_bf16_f32 v0, v14, v15
	v_cvt_pk_bf16_f32 v1, v12, v13
	v_cvt_pk_bf16_f32 v2, v38, v39
	v_cvt_pk_bf16_f32 v3, v36, v37
	global_store_dwordx2 v[66:67], v[0:1], off offset:1536
	global_store_dwordx2 v[68:69], v[2:3], off offset:1536
	s_nop 0
	v_mul_f32_e32 v79, v14, v14
	v_mul_f32_e32 v83, v15, v15
	v_mul_f32_e32 v85, v12, v12
	v_mul_f32_e32 v99, v13, v13
	v_mul_f32_e32 v101, v38, v38
	v_mul_f32_e32 v103, v39, v39
	v_mul_f32_e32 v77, v36, v36
	v_mul_f32_e32 v75, v37, v37
	v_pk_add_f32 v[66:67], v[78:79], v[82:83]
	v_pk_add_f32 v[68:69], v[84:85], v[98:99]
	v_pk_add_f32 v[78:79], v[100:101], v[102:103]
	v_pk_add_f32 v[74:75], v[76:77], v[74:75]
	v_pk_add_f32 v[66:67], v[66:67], v[68:69]
	v_pk_add_f32 v[68:69], v[78:79], v[74:75]
	v_mov_b32_e32 v75, v66
	v_mov_b32_e32 v74, v68
	v_mov_b32_e32 v66, v69
	v_pk_add_f32 v[66:67], v[74:75], v[66:67]
	s_waitcnt lgkmcnt(0)
	s_waitcnt lgkmcnt(0)
	s_waitcnt lgkmcnt(0)
	s_waitcnt lgkmcnt(0)
	s_waitcnt lgkmcnt(0)
	s_waitcnt lgkmcnt(0)
	s_nop 1
	v_add_f32_dpp v66, v66, v66 row_ror:8 row_mask:0xf bank_mask:0xf
	v_add_f32_dpp v67, v67, v67 row_ror:8 row_mask:0xf bank_mask:0xf
	s_nop 0
	v_add_f32_dpp v66, v66, v66 row_ror:4 row_mask:0xf bank_mask:0xf
	v_add_f32_dpp v67, v67, v67 row_ror:4 row_mask:0xf bank_mask:0xf
	s_nop 0
	v_add_f32_dpp v66, v66, v66 row_ror:2 row_mask:0xf bank_mask:0xf
	v_add_f32_dpp v67, v67, v67 row_ror:2 row_mask:0xf bank_mask:0xf
	s_nop 0
	v_add_f32_dpp v66, v66, v66 row_ror:1 row_mask:0xf bank_mask:0xf
	v_add_f32_dpp v67, v67, v67 row_ror:1 row_mask:0xf bank_mask:0xf
	v_mov_b32_e32 v68, v66
	v_mov_b32_e32 v69, v67
	s_nop 1
	v_permlane16_swap_b32 v66, v68
	v_permlane16_swap_b32 v67, v69
	s_nop 1
	v_add_f32_e32 v66, v66, v68
	v_add_f32_e32 v67, v67, v69
	v_mov_b32_e32 v68, v66
	v_mov_b32_e32 v69, v67
	s_nop 1
	v_permlane32_swap_b32 v66, v68
	v_permlane32_swap_b32 v67, v69
	s_nop 1
	v_pk_add_f32 v[66:67], v[66:67], v[68:69]
	s_nop 0
	v_pk_fma_f32 v[66:67], v[66:67], s[8:9], v[64:65] op_sel_hi:[1,0,0]
	s_add_i32 s9, s9, s20
	v_mul_f32_e32 v68, 0x4b800000, v67
	v_cmp_gt_f32_e64 s[0:1], s24, v67
	v_mul_f32_e32 v69, 0x4b800000, v66
	v_cmp_gt_f32_e32 vcc, s24, v66
	v_cndmask_b32_e64 v67, v67, v68, s[0:1]
	v_rsq_f32_e32 v67, v67
	v_cndmask_b32_e32 v66, v66, v69, vcc
	v_rsq_f32_e32 v68, v66
	s_cmp_lt_i32 s9, 0x8000
	v_mul_f32_e32 v66, 0x45800000, v67
	v_cndmask_b32_e64 v66, v67, v66, s[0:1]
	v_mul_f32_e32 v69, 0x45800000, v68
	v_cndmask_b32_e32 v68, v68, v69, vcc
	v_pk_mul_f32 v[74:75], v[86:87], v[66:67] op_sel_hi:[1,0]
	v_pk_mul_f32 v[72:73], v[72:73], v[66:67] op_sel_hi:[1,0]
	v_pk_add_f32 v[2:3], v[178:179], 1.0 op_sel_hi:[1,0]
	v_pk_add_f32 v[0:1], v[176:177], 1.0 op_sel_hi:[1,0]
	v_pk_mul_f32 v[2:3], v[182:183], v[2:3]
	v_pk_mul_f32 v[0:1], v[180:181], v[0:1]
	v_pk_mul_f32 v[32:33], v[32:33], v[68:69] op_sel_hi:[1,0]
	v_pk_mul_f32 v[34:35], v[34:35], v[68:69] op_sel_hi:[1,0]
	v_pk_fma_f32 v[4:5], v[2:3], v[72:73], v[186:187]
	v_pk_fma_f32 v[6:7], v[0:1], v[74:75], v[184:185]
	v_pk_fma_f32 v[2:3], v[2:3], v[34:35], v[186:187]
	v_pk_fma_f32 v[0:1], v[0:1], v[32:33], v[184:185]
	v_cvt_pk_bf16_f32 v6, v6, v7
	v_cvt_pk_bf16_f32 v7, v4, v5
	v_cvt_pk_bf16_f32 v0, v0, v1
	v_cvt_pk_bf16_f32 v1, v2, v3
	global_store_dwordx2 v[70:71], v[6:7], off
	global_store_dwordx2 v[70:71], v[0:1], off offset:2048
	s_nop 0
	v_pk_mul_f32 v[30:31], v[30:31], v[66:67] op_sel_hi:[1,0]
	v_pk_mul_f32 v[28:29], v[28:29], v[66:67] op_sel_hi:[1,0]
	v_pk_mul_f32 v[24:25], v[24:25], v[68:69] op_sel_hi:[1,0]
	v_pk_mul_f32 v[26:27], v[26:27], v[68:69] op_sel_hi:[1,0]
	v_pk_mul_f32 v[22:23], v[22:23], v[66:67] op_sel_hi:[1,0]
	v_pk_mul_f32 v[20:21], v[20:21], v[66:67] op_sel_hi:[1,0]
	v_pk_mul_f32 v[16:17], v[16:17], v[68:69] op_sel_hi:[1,0]
	v_pk_mul_f32 v[18:19], v[18:19], v[68:69] op_sel_hi:[1,0]
	v_pk_mul_f32 v[14:15], v[14:15], v[66:67] op_sel_hi:[1,0]
	v_pk_mul_f32 v[12:13], v[12:13], v[66:67] op_sel_hi:[1,0]
	v_pk_add_f32 v[2:3], v[190:191], 1.0 op_sel_hi:[1,0]
	v_pk_add_f32 v[0:1], v[188:189], 1.0 op_sel_hi:[1,0]
	v_pk_mul_f32 v[2:3], v[194:195], v[2:3]
	v_pk_mul_f32 v[0:1], v[192:193], v[0:1]
	v_pk_fma_f32 v[4:5], v[2:3], v[28:29], v[198:199]
	v_pk_fma_f32 v[6:7], v[0:1], v[30:31], v[196:197]
	v_pk_fma_f32 v[2:3], v[2:3], v[26:27], v[198:199]
	v_pk_fma_f32 v[0:1], v[0:1], v[24:25], v[196:197]
	v_cvt_pk_bf16_f32 v6, v6, v7
	v_cvt_pk_bf16_f32 v7, v4, v5
	v_cvt_pk_bf16_f32 v0, v0, v1
	v_cvt_pk_bf16_f32 v1, v2, v3
	global_store_dwordx2 v[70:71], v[6:7], off offset:512
	global_store_dwordx2 v[70:71], v[0:1], off offset:2560
	s_nop 0
	v_pk_add_f32 v[2:3], v[202:203], 1.0 op_sel_hi:[1,0]
	v_pk_add_f32 v[0:1], v[200:201], 1.0 op_sel_hi:[1,0]
	v_pk_mul_f32 v[2:3], v[206:207], v[2:3]
	v_pk_mul_f32 v[0:1], v[204:205], v[0:1]
	v_pk_fma_f32 v[4:5], v[20:21], v[2:3], v[222:223]
	v_pk_fma_f32 v[6:7], v[22:23], v[0:1], v[220:221]
	v_pk_fma_f32 v[2:3], v[18:19], v[2:3], v[222:223]
	v_pk_fma_f32 v[0:1], v[16:17], v[0:1], v[220:221]
	v_cvt_pk_bf16_f32 v6, v6, v7
	v_cvt_pk_bf16_f32 v7, v4, v5
	v_cvt_pk_bf16_f32 v0, v0, v1
	v_cvt_pk_bf16_f32 v1, v2, v3
	global_store_dwordx2 v[70:71], v[6:7], off offset:1024
	global_store_dwordx2 v[70:71], v[0:1], off offset:3072
	s_nop 0
	v_pk_mul_f32 v[16:17], v[38:39], v[68:69] op_sel_hi:[1,0]
	v_pk_mul_f32 v[18:19], v[36:37], v[68:69] op_sel_hi:[1,0]
	v_pk_add_f32 v[2:3], v[226:227], 1.0 op_sel_hi:[1,0]
	v_pk_add_f32 v[0:1], v[224:225], 1.0 op_sel_hi:[1,0]
	v_pk_mul_f32 v[2:3], v[230:231], v[2:3]
	v_pk_mul_f32 v[0:1], v[228:229], v[0:1]
	v_pk_fma_f32 v[4:5], v[12:13], v[2:3], v[234:235]
	v_pk_fma_f32 v[6:7], v[14:15], v[0:1], v[232:233]
	v_pk_fma_f32 v[2:3], v[18:19], v[2:3], v[234:235]
	v_pk_fma_f32 v[0:1], v[16:17], v[0:1], v[232:233]
	v_cvt_pk_bf16_f32 v6, v6, v7
	v_cvt_pk_bf16_f32 v7, v4, v5
	v_cvt_pk_bf16_f32 v0, v0, v1
	v_cvt_pk_bf16_f32 v1, v2, v3
	global_store_dwordx2 v[70:71], v[6:7], off offset:1536
	global_store_dwordx2 v[70:71], v[0:1], off offset:3584
	s_cbranch_scc1 .LBB0_316

.LBB0_912:
	s_ashr_i32 s98, s2, 11
	s_mul_i32 s98, s98, 9
	s_ashr_i32 s99, s98, 31
	s_lshl_b64 s[98:99], s[98:99], 12
	s_add_u32 s98, s14, s98
	s_addc_u32 s99, s15, s99
	s_add_u32 s98, s98, 0x5000
	s_addc_u32 s99, s99, 0
	s_and_b32 s0, s18, 0x8000
	s_and_b32 s1, s7, 0xfffff000
	s_add_i32 s0, s0, s1
	s_and_b32 s1, s4, 0xffc
	s_or_b32 s0, s0, s1
	s_ashr_i32 s1, s0, 31
	s_lshl_b64 s[0:1], s[0:1], 11
	s_ashr_i32 s5, s4, 31
	v_lshl_add_u64 v[64:65], v[4:5], 0, s[0:1]
	s_lshl_b64 s[10:11], s[4:5], 11
	v_lshl_add_u64 v[0:1], v[6:7], 0, s[10:11]
	global_load_dwordx2 v[80:81], v[64:65], off
	global_load_dwordx2 v[2:3], v[0:1], off
	s_add_i32 s0, s4, 1
	s_ashr_i32 s1, s0, 31
	s_lshl_b64 s[0:1], s[0:1], 11
	v_lshl_add_u64 v[40:41], v[6:7], 0, s[0:1]
	s_add_i32 s0, s4, 2
	s_ashr_i32 s1, s0, 31
	s_lshl_b64 s[0:1], s[0:1], 11
	v_lshl_add_u64 v[88:89], v[6:7], 0, s[0:1]
	s_movk_i32 s0, 0x1000
	v_add_co_u32_e32 v90, vcc, s0, v64
	s_add_i32 s0, s4, 3
	s_nop 0
	v_addc_co_u32_e32 v91, vcc, 0, v65, vcc
	s_ashr_i32 s1, s0, 31
	s_lshl_b64 s[0:1], s[0:1], 11
	v_lshl_add_u64 v[106:107], v[6:7], 0, s[0:1]
	s_mov_b32 s17, s11
	global_load_dwordx2 v[82:83], v[64:65], off offset:512
	global_load_dwordx2 v[202:203], v[0:1], off offset:512
	global_load_dwordx2 v[84:85], v[64:65], off offset:1024
	global_load_dwordx2 v[204:205], v[0:1], off offset:1024
	global_load_dwordx2 v[86:87], v[64:65], off offset:1536
	global_load_dwordx2 v[32:33], v[0:1], off offset:1536
	global_load_dwordx2 v[96:97], v[64:65], off offset:2048
	global_load_dwordx2 v[44:45], v[40:41], off
	global_load_dwordx2 v[126:127], v[64:65], off offset:2560
	global_load_dwordx2 v[206:207], v[40:41], off offset:512
	global_load_dwordx2 v[128:129], v[64:65], off offset:3072
	global_load_dwordx2 v[220:221], v[40:41], off offset:1024
	global_load_dwordx2 v[140:141], v[64:65], off offset:3584
	global_load_dwordx2 v[46:47], v[40:41], off offset:1536
	global_load_dwordx2 v[98:99], v[90:91], off
	global_load_dwordx2 v[64:65], v[88:89], off
	global_load_dwordx2 v[100:101], v[90:91], off offset:512
	global_load_dwordx2 v[222:223], v[88:89], off offset:512
	global_load_dwordx2 v[142:143], v[90:91], off offset:1024
	global_load_dwordx2 v[224:225], v[88:89], off offset:1024
	global_load_dwordx2 v[148:149], v[90:91], off offset:1536
	global_load_dwordx2 v[76:77], v[88:89], off offset:1536
	global_load_dwordx2 v[150:151], v[90:91], off offset:2048
	global_load_dwordx2 v[78:79], v[106:107], off
	global_load_dwordx2 v[152:153], v[90:91], off offset:2560
	global_load_dwordx2 v[92:93], v[106:107], off offset:512
	global_load_dwordx2 v[160:161], v[90:91], off offset:3072
	global_load_dwordx2 v[226:227], v[106:107], off offset:1024
	global_load_dwordx2 v[174:175], v[90:91], off offset:3584
	global_load_dwordx2 v[90:91], v[106:107], off offset:1536
	global_load_dwordx4 v[228:231], v190, s[98:99]
	global_load_dwordx4 v[198:201], v[10:11], off
	global_load_dwordx4 v[232:235], v191, s[98:99]
	global_load_dwordx4 v[236:239], v[12:13], off
	global_load_dwordx4 v[240:243], v192, s[98:99]
	global_load_dwordx4 v[244:247], v[14:15], off
	global_load_dwordx4 v[212:215], v193, s[98:99]
	global_load_dwordx4 v[216:219], v[16:17], off
	s_waitcnt vmcnt(0)
	v_lshlrev_b32_e32 v48, 16, v2
	v_and_b32_e32 v49, 0xffff0000, v2
	v_lshlrev_b32_e32 v50, 16, v3
	v_and_b32_e32 v51, 0xffff0000, v3
	v_lshlrev_b32_e32 v38, 16, v202
	v_and_b32_e32 v39, 0xffff0000, v202
	v_lshlrev_b32_e32 v42, 16, v203
	v_and_b32_e32 v43, 0xffff0000, v203
	v_lshlrev_b32_e32 v132, 16, v84
	v_and_b32_e32 v133, 0xffff0000, v84
	v_lshlrev_b32_e32 v134, 16, v85
	v_lshlrev_b32_e32 v60, 16, v44
	v_and_b32_e32 v61, 0xffff0000, v44
	v_lshlrev_b32_e32 v62, 16, v45
	v_and_b32_e32 v63, 0xffff0000, v45
	v_and_b32_e32 v135, 0xffff0000, v85
	v_lshlrev_b32_e32 v121, 16, v86
	v_and_b32_e32 v119, 0xffff0000, v86
	v_mul_f32_e32 v118, v119, v119
	v_lshlrev_b32_e32 v34, 16, v204
	v_and_b32_e32 v35, 0xffff0000, v204
	v_lshlrev_b32_e32 v36, 16, v205
	v_and_b32_e32 v37, 0xffff0000, v205
	v_lshlrev_b32_e32 v2, 16, v32
	v_and_b32_e32 v3, 0xffff0000, v32
	v_lshlrev_b32_e32 v32, 16, v33
	v_and_b32_e32 v33, 0xffff0000, v33
	v_lshlrev_b32_e32 v56, 16, v206
	v_and_b32_e32 v57, 0xffff0000, v206
	v_lshlrev_b32_e32 v58, 16, v207
	v_and_b32_e32 v59, 0xffff0000, v207
	s_nop 0
	v_lshlrev_b32_e32 v138, 16, v129
	v_and_b32_e32 v139, 0xffff0000, v129
	v_and_b32_e32 v129, 0xffff0000, v140
	v_lshlrev_b32_e32 v72, 16, v64
	v_and_b32_e32 v73, 0xffff0000, v64
	v_lshlrev_b32_e32 v74, 16, v65
	v_and_b32_e32 v75, 0xffff0000, v65
	v_lshlrev_b32_e32 v176, 16, v98
	v_and_b32_e32 v177, 0xffff0000, v98
	v_lshlrev_b32_e32 v98, 16, v99
	v_and_b32_e32 v99, 0xffff0000, v99
	v_lshlrev_b32_e32 v52, 16, v220
	v_and_b32_e32 v53, 0xffff0000, v220
	v_lshlrev_b32_e32 v54, 16, v221
	v_and_b32_e32 v55, 0xffff0000, v221
	v_lshlrev_b32_e32 v44, 16, v46
	v_and_b32_e32 v45, 0xffff0000, v46
	v_lshlrev_b32_e32 v46, 16, v47
	v_and_b32_e32 v47, 0xffff0000, v47
	v_and_b32_e32 v165, 0xffff0000, v101
	v_lshlrev_b32_e32 v66, 16, v222
	v_and_b32_e32 v67, 0xffff0000, v222
	v_lshlrev_b32_e32 v68, 16, v223
	v_and_b32_e32 v69, 0xffff0000, v223
	v_and_b32_e32 v164, 0xffff0000, v100
	v_lshlrev_b32_e32 v163, 16, v101
	v_lshlrev_b32_e32 v162, 16, v100
	v_pk_mul_f32 v[100:101], v[164:165], v[164:165]
	v_lshlrev_b32_e32 v70, 16, v224
	v_pk_fma_f32 v[100:101], v[162:163], v[162:163], v[100:101]
	v_and_b32_e32 v181, 0xffff0000, v151
	v_lshlrev_b32_e32 v122, 16, v92
	v_and_b32_e32 v123, 0xffff0000, v92
	v_lshlrev_b32_e32 v124, 16, v93
	v_and_b32_e32 v125, 0xffff0000, v93
	s_nop 0
	v_pk_add_f32 v[100:101], v[100:101], v[100:101] op_sel:[0,1] op_sel_hi:[1,0]
	v_and_b32_e32 v179, 0xffff0000, v150
	v_lshlrev_b32_e32 v180, 16, v151
	v_and_b32_e32 v173, 0xffff0000, v153
	v_lshlrev_b32_e32 v178, 16, v150
	v_lshlrev_b32_e32 v102, 16, v76
	v_and_b32_e32 v103, 0xffff0000, v76
	v_lshlrev_b32_e32 v104, 16, v77
	v_and_b32_e32 v105, 0xffff0000, v77
	v_lshlrev_b32_e32 v76, 16, v78
	v_and_b32_e32 v77, 0xffff0000, v78
	v_lshlrev_b32_e32 v78, 16, v79
	v_and_b32_e32 v79, 0xffff0000, v79
	v_and_b32_e32 v71, 0xffff0000, v224
	v_lshlrev_b32_e32 v64, 16, v225
	v_and_b32_e32 v65, 0xffff0000, v225
	v_and_b32_e32 v151, 0xffff0000, v174
	v_lshlrev_b32_e32 v114, 16, v227
	v_and_b32_e32 v115, 0xffff0000, v227
	v_and_b32_e32 v93, 0xffff0000, v81
	v_lshlrev_b32_e32 v112, 16, v226
	v_and_b32_e32 v113, 0xffff0000, v226
	v_lshlrev_b32_e32 v108, 16, v90
	v_and_b32_e32 v109, 0xffff0000, v90
	v_lshlrev_b32_e32 v110, 16, v91
	v_and_b32_e32 v111, 0xffff0000, v91
	v_lshlrev_b32_e32 v90, 16, v80
	v_and_b32_e32 v91, 0xffff0000, v80
	v_lshlrev_b32_e32 v92, 16, v81
	v_mul_f32_e32 v80, v93, v93
	v_pk_fma_f32 v[94:95], v[92:93], v[92:93], v[80:81] op_sel_hi:[1,1,0]
	v_lshlrev_b32_e32 v81, 16, v83
	v_lshlrev_b32_e32 v80, 16, v82
	v_and_b32_e32 v83, 0xffff0000, v83
	v_and_b32_e32 v82, 0xffff0000, v82
	v_mul_f32_e32 v84, v91, v91
	v_pk_mul_f32 v[116:117], v[82:83], v[82:83]
	v_pk_fma_f32 v[84:85], v[90:91], v[90:91], v[84:85] op_sel_hi:[1,1,0]
	v_pk_fma_f32 v[130:131], v[80:81], v[80:81], v[116:117]
	v_lshlrev_b32_e32 v116, 16, v87
	v_and_b32_e32 v117, 0xffff0000, v87
	v_mov_b32_e32 v120, v84
	v_mov_b32_e32 v86, v94
	v_mov_b32_e32 v87, v121
	v_pk_add_f32 v[84:85], v[84:85], v[94:95]
	v_pk_mul_f32 v[86:87], v[120:121], v[86:87]
	v_mul_f32_e32 v94, v135, v135
	v_mov_b32_e32 v85, v87
	v_pk_add_f32 v[86:87], v[130:131], v[130:131] op_sel:[0,1] op_sel_hi:[1,0]
	v_mul_f32_e32 v136, v116, v116
	v_mov_b32_e32 v87, v118
	v_pk_add_f32 v[84:85], v[84:85], v[86:87]
	v_mul_f32_e32 v86, v133, v133
	v_mul_f32_e32 v137, v117, v117
	v_pk_fma_f32 v[86:87], v[132:133], v[132:133], v[86:87] op_sel_hi:[1,1,0]
	v_pk_fma_f32 v[94:95], v[134:135], v[134:135], v[94:95] op_sel_hi:[1,1,0]
	v_mov_b32_e32 v87, v136
	v_mov_b32_e32 v95, v137
	v_pk_add_f32 v[86:87], v[86:87], v[94:95]
	v_lshlrev_b32_e32 v94, 16, v96
	v_and_b32_e32 v95, 0xffff0000, v96
	v_lshlrev_b32_e32 v96, 16, v97
	v_and_b32_e32 v97, 0xffff0000, v97
	v_pk_add_f32 v[144:145], v[84:85], v[86:87]
	v_mul_f32_e32 v84, v97, v97
	v_and_b32_e32 v87, 0xffff0000, v127
	v_and_b32_e32 v86, 0xffff0000, v126
	v_pk_fma_f32 v[146:147], v[96:97], v[96:97], v[84:85] op_sel_hi:[1,1,0]
	v_lshlrev_b32_e32 v85, 16, v127
	v_lshlrev_b32_e32 v84, 16, v126
	v_pk_mul_f32 v[126:127], v[86:87], v[86:87]
	v_mul_f32_e32 v118, v95, v95
	v_pk_fma_f32 v[154:155], v[84:85], v[84:85], v[126:127]
	v_lshlrev_b32_e32 v131, 16, v140
	v_lshlrev_b32_e32 v126, 16, v141
	v_and_b32_e32 v127, 0xffff0000, v141
	v_pk_fma_f32 v[140:141], v[94:95], v[94:95], v[118:119] op_sel_hi:[1,1,0]
	v_mov_b32_e32 v156, v146
	v_mov_b32_e32 v130, v140
	v_mov_b32_e32 v157, v131
	v_pk_add_f32 v[140:141], v[140:141], v[146:147]
	v_pk_mul_f32 v[146:147], v[130:131], v[156:157]
	v_and_b32_e32 v137, 0xffff0000, v128
	v_mul_f32_e32 v120, v129, v129
	v_mov_b32_e32 v141, v147
	v_pk_add_f32 v[146:147], v[154:155], v[154:155] op_sel:[0,1] op_sel_hi:[1,0]
	v_lshlrev_b32_e32 v136, 16, v128
	v_mov_b32_e32 v147, v120
	v_mul_f32_e32 v118, v137, v137
	v_pk_add_f32 v[140:141], v[140:141], v[146:147]
	v_pk_fma_f32 v[146:147], v[136:137], v[136:137], v[118:119] op_sel_hi:[1,1,0]
	v_mul_f32_e32 v118, v139, v139
	v_mul_f32_e32 v128, v126, v126
	v_mul_f32_e32 v158, v127, v127
	v_pk_fma_f32 v[154:155], v[138:139], v[138:139], v[118:119] op_sel_hi:[1,1,0]
	v_mov_b32_e32 v147, v128
	v_mov_b32_e32 v155, v158
	v_pk_add_f32 v[146:147], v[146:147], v[154:155]
	v_lshlrev_b32_e32 v154, 16, v142
	v_pk_add_f32 v[140:141], v[140:141], v[146:147]
	v_mov_b32_e32 v147, v144
	v_mov_b32_e32 v146, v140
	v_mov_b32_e32 v144, v141
	v_pk_add_f32 v[140:141], v[146:147], v[144:145]
	v_and_b32_e32 v155, 0xffff0000, v142
	v_lshlrev_b32_e32 v156, 16, v143
	v_and_b32_e32 v157, 0xffff0000, v143
	v_lshlrev_b32_e32 v147, 16, v148
	s_waitcnt lgkmcnt(0)
	v_lshlrev_b32_e32 v142, 16, v149
	v_and_b32_e32 v143, 0xffff0000, v149
	v_mov_b32_e32 v167, v147
	v_mul_f32_e32 v172, v143, v143
	s_waitcnt lgkmcnt(0)
	s_waitcnt lgkmcnt(0)
	s_waitcnt lgkmcnt(0)
	s_waitcnt lgkmcnt(0)
	s_waitcnt lgkmcnt(0)
	s_nop 1
	v_add_f32_dpp v140, v140, v140 row_ror:8 row_mask:0xf bank_mask:0xf
	v_add_f32_dpp v141, v141, v141 row_ror:8 row_mask:0xf bank_mask:0xf
	s_nop 0
	v_add_f32_dpp v140, v140, v140 row_ror:4 row_mask:0xf bank_mask:0xf
	v_add_f32_dpp v141, v141, v141 row_ror:4 row_mask:0xf bank_mask:0xf
	s_nop 0
	v_add_f32_dpp v140, v140, v140 row_ror:2 row_mask:0xf bank_mask:0xf
	v_add_f32_dpp v141, v141, v141 row_ror:2 row_mask:0xf bank_mask:0xf
	s_nop 0
	v_add_f32_dpp v140, v140, v140 row_ror:1 row_mask:0xf bank_mask:0xf
	v_add_f32_dpp v141, v141, v141 row_ror:1 row_mask:0xf bank_mask:0xf
	v_mov_b32_e32 v144, v140
	v_mov_b32_e32 v145, v141
	s_nop 1
	v_permlane16_swap_b32 v140, v144
	v_permlane16_swap_b32 v141, v145
	s_nop 1
	v_add_f32_e32 v140, v140, v144
	v_add_f32_e32 v141, v141, v145
	v_mov_b32_e32 v144, v140
	v_mov_b32_e32 v145, v141
	s_nop 1
	v_permlane32_swap_b32 v140, v144
	v_permlane32_swap_b32 v141, v145
	s_nop 1
	v_pk_add_f32 v[144:145], v[140:141], v[144:145]
	v_mov_b64_e32 v[140:141], s[8:9]
	v_pk_fma_f32 v[144:145], v[144:145], s[6:7], v[140:141] op_sel_hi:[1,0,0]
	s_nop 0
	v_mul_f32_e32 v118, 0x4b800000, v145
	v_cmp_gt_f32_e64 s[0:1], s21, v145
	v_cmp_gt_f32_e32 vcc, s21, v144
	s_nop 0
	v_cndmask_b32_e64 v118, v145, v118, s[0:1]
	v_rsq_f32_e32 v118, v118
	v_and_b32_e32 v145, 0xffff0000, v148
	v_mul_f32_e32 v130, v145, v145
	v_mov_b32_e32 v101, v130
	v_mul_f32_e32 v120, 0x45800000, v118
	v_cndmask_b32_e64 v128, v118, v120, s[0:1]
	v_mul_f32_e32 v118, 0x4b800000, v144
	v_cndmask_b32_e32 v118, v144, v118, vcc
	v_rsq_f32_e32 v118, v118
	v_mul_f32_e32 v144, v142, v142
	v_mul_f32_e32 v130, v151, v151
	v_pk_mul_f32 v[90:91], v[128:129], v[90:91] op_sel_hi:[0,1]
	v_mul_f32_e32 v120, 0x45800000, v118
	v_cndmask_b32_e32 v120, v118, v120, vcc
	v_mul_f32_e32 v118, v99, v99
	v_pk_fma_f32 v[158:159], v[98:99], v[98:99], v[118:119] op_sel_hi:[1,1,0]
	v_mul_f32_e32 v118, v177, v177
	v_pk_fma_f32 v[148:149], v[176:177], v[176:177], v[118:119] op_sel_hi:[1,1,0]
	v_mov_b32_e32 v166, v158
	v_mov_b32_e32 v146, v148
	v_pk_add_f32 v[148:149], v[148:149], v[158:159]
	v_pk_mul_f32 v[158:159], v[146:147], v[166:167]
	v_mul_f32_e32 v118, v155, v155
	v_mov_b32_e32 v149, v159
	v_pk_add_f32 v[100:101], v[148:149], v[100:101]
	v_pk_fma_f32 v[148:149], v[154:155], v[154:155], v[118:119] op_sel_hi:[1,1,0]
	v_mul_f32_e32 v118, v157, v157
	v_pk_fma_f32 v[158:159], v[156:157], v[156:157], v[118:119] op_sel_hi:[1,1,0]
	v_mov_b32_e32 v149, v144
	v_mov_b32_e32 v159, v172
	v_pk_add_f32 v[148:149], v[148:149], v[158:159]
	v_mul_f32_e32 v118, v181, v181
	v_and_b32_e32 v172, 0xffff0000, v152
	v_pk_add_f32 v[100:101], v[100:101], v[148:149]
	v_pk_fma_f32 v[182:183], v[180:181], v[180:181], v[118:119] op_sel_hi:[1,1,0]
	v_lshlrev_b32_e32 v167, 16, v153
	v_lshlrev_b32_e32 v166, 16, v152
	v_pk_mul_f32 v[148:149], v[172:173], v[172:173]
	v_mul_f32_e32 v118, v179, v179
	v_pk_fma_f32 v[194:195], v[166:167], v[166:167], v[148:149]
	v_lshlrev_b32_e32 v153, 16, v174
	v_lshlrev_b32_e32 v148, 16, v175
	v_and_b32_e32 v149, 0xffff0000, v175
	v_pk_fma_f32 v[174:175], v[178:179], v[178:179], v[118:119] op_sel_hi:[1,1,0]
	v_mov_b32_e32 v196, v182
	v_mov_b32_e32 v152, v174
	v_mov_b32_e32 v197, v153
	v_pk_add_f32 v[174:175], v[174:175], v[182:183]
	v_pk_mul_f32 v[182:183], v[152:153], v[196:197]
	v_and_b32_e32 v159, 0xffff0000, v160
	v_mov_b32_e32 v175, v183
	v_pk_add_f32 v[182:183], v[194:195], v[194:195] op_sel:[0,1] op_sel_hi:[1,0]
	v_lshlrev_b32_e32 v158, 16, v160
	v_lshlrev_b32_e32 v160, 16, v161
	v_and_b32_e32 v161, 0xffff0000, v161
	v_mov_b32_e32 v183, v130
	v_mul_f32_e32 v118, v159, v159
	v_pk_add_f32 v[174:175], v[174:175], v[182:183]
	v_pk_fma_f32 v[182:183], v[158:159], v[158:159], v[118:119] op_sel_hi:[1,1,0]
	v_mul_f32_e32 v118, v161, v161
	v_mul_f32_e32 v144, v148, v148
	v_mul_f32_e32 v146, v149, v149
	v_pk_fma_f32 v[194:195], v[160:161], v[160:161], v[118:119] op_sel_hi:[1,1,0]
	v_mov_b32_e32 v183, v144
	v_mov_b32_e32 v195, v146
	v_pk_add_f32 v[182:183], v[182:183], v[194:195]
	v_pk_mul_f32 v[92:93], v[128:129], v[92:93] op_sel_hi:[0,1]
	v_pk_add_f32 v[174:175], v[174:175], v[182:183]
	v_mov_b32_e32 v183, v100
	v_mov_b32_e32 v182, v174
	v_mov_b32_e32 v100, v175
	v_pk_add_f32 v[100:101], v[182:183], v[100:101]
	v_mov_b32_e32 v144, v147
	v_mov_b32_e32 v150, v153
	s_waitcnt lgkmcnt(0)
	s_waitcnt lgkmcnt(0)
	s_waitcnt lgkmcnt(0)
	s_waitcnt lgkmcnt(0)
	s_waitcnt lgkmcnt(0)
	s_waitcnt lgkmcnt(0)
	s_nop 1
	v_add_f32_dpp v100, v100, v100 row_ror:8 row_mask:0xf bank_mask:0xf
	v_add_f32_dpp v101, v101, v101 row_ror:8 row_mask:0xf bank_mask:0xf
	s_nop 0
	v_add_f32_dpp v100, v100, v100 row_ror:4 row_mask:0xf bank_mask:0xf
	v_add_f32_dpp v101, v101, v101 row_ror:4 row_mask:0xf bank_mask:0xf
	s_nop 0
	v_add_f32_dpp v100, v100, v100 row_ror:2 row_mask:0xf bank_mask:0xf
	v_add_f32_dpp v101, v101, v101 row_ror:2 row_mask:0xf bank_mask:0xf
	s_nop 0
	v_add_f32_dpp v100, v100, v100 row_ror:1 row_mask:0xf bank_mask:0xf
	v_add_f32_dpp v101, v101, v101 row_ror:1 row_mask:0xf bank_mask:0xf
	v_mov_b32_e32 v174, v100
	v_mov_b32_e32 v175, v101
	s_nop 1
	v_permlane16_swap_b32 v100, v174
	v_permlane16_swap_b32 v101, v175
	s_nop 1
	v_add_f32_e32 v100, v100, v174
	v_add_f32_e32 v101, v101, v175
	v_mov_b32_e32 v174, v100
	v_mov_b32_e32 v175, v101
	s_nop 1
	v_permlane32_swap_b32 v100, v174
	v_permlane32_swap_b32 v101, v175
	s_nop 1
	v_pk_add_f32 v[100:101], v[100:101], v[174:175]
	s_nop 0
	v_pk_fma_f32 v[100:101], v[100:101], s[6:7], v[140:141] op_sel_hi:[1,0,0]
	s_nop 0
	v_mul_f32_e32 v118, 0x4b800000, v101
	v_cmp_gt_f32_e64 s[0:1], s21, v101
	v_cmp_gt_f32_e32 vcc, s21, v100
	s_nop 0
	v_cndmask_b32_e64 v101, v101, v118, s[0:1]
	v_rsq_f32_e32 v101, v101
	s_nop 0
	v_mul_f32_e32 v118, 0x45800000, v101
	v_cndmask_b32_e64 v146, v101, v118, s[0:1]
	s_ashr_i32 s0, s2, 11
	s_mul_i32 s0, s0, 9
	s_ashr_i32 s1, s0, 31
	s_lshl_b64 s[0:1], s[0:1], 12
	s_add_u32 s5, s14, s0
	s_addc_u32 s13, s15, s1
	s_add_u32 s0, s5, 0x5000
	s_addc_u32 s1, s13, 0
	v_mul_f32_e32 v101, 0x4b800000, v100
	v_cndmask_b32_e32 v100, v100, v101, vcc
	v_rsq_f32_e32 v100, v100
	v_mov_b32_e32 v118, v121
	v_mul_f32_e32 v101, 0x45800000, v100
	v_cndmask_b32_e32 v130, v100, v101, vcc
	v_pk_mul_f32 v[196:197], v[230:231], v[200:201]
	v_pk_mul_f32 v[194:195], v[228:229], v[198:199]
	v_pk_fma_f32 v[174:175], v[92:93], v[196:197], v[50:51]
	v_pk_fma_f32 v[182:183], v[90:91], v[194:195], v[48:49]
	v_cvt_pk_bf16_f32 v49, v174, v175
	v_cvt_pk_bf16_f32 v48, v182, v183
	global_store_dwordx2 v[0:1], v[48:49], off
	v_pk_mul_f32 v[48:49], v[174:175], v[174:175]
	v_pk_mul_f32 v[50:51], v[182:183], v[182:183]
	s_nop 0
	v_pk_mov_b32 v[90:91], v[50:51], v[48:49] op_sel:[1,0]
	v_mov_b32_e32 v51, v49
	v_pk_add_f32 v[198:199], v[90:91], v[50:51]
	v_pk_mul_f32 v[48:49], v[120:121], v[94:95] op_sel_hi:[0,1]
	v_pk_mul_f32 v[50:51], v[120:121], v[96:97] op_sel_hi:[0,1]
	v_pk_fma_f32 v[94:95], v[50:51], v[196:197], v[62:63]
	v_pk_fma_f32 v[96:97], v[48:49], v[194:195], v[60:61]
	v_cvt_pk_bf16_f32 v49, v94, v95
	v_cvt_pk_bf16_f32 v48, v96, v97
	global_store_dwordx2 v[40:41], v[48:49], off
	v_pk_mul_f32 v[48:49], v[94:95], v[94:95]
	v_pk_mul_f32 v[50:51], v[96:97], v[96:97]
	s_nop 0
	v_pk_mov_b32 v[60:61], v[50:51], v[48:49] op_sel:[1,0]
	v_mov_b32_e32 v51, v49
	v_pk_add_f32 v[200:201], v[60:61], v[50:51]
	v_pk_mul_f32 v[48:49], v[146:147], v[176:177] op_sel_hi:[0,1]
	v_pk_mul_f32 v[50:51], v[146:147], v[98:99] op_sel_hi:[0,1]
	v_pk_fma_f32 v[98:99], v[196:197], v[50:51], v[74:75]
	v_pk_fma_f32 v[100:101], v[194:195], v[48:49], v[72:73]
	v_cvt_pk_bf16_f32 v49, v98, v99
	v_cvt_pk_bf16_f32 v48, v100, v101
	global_store_dwordx2 v[88:89], v[48:49], off
	v_pk_mul_f32 v[48:49], v[98:99], v[98:99]
	v_pk_mul_f32 v[50:51], v[100:101], v[100:101]
	s_nop 0
	v_pk_mov_b32 v[60:61], v[50:51], v[48:49] op_sel:[1,0]
	v_mov_b32_e32 v51, v49
	v_pk_add_f32 v[176:177], v[60:61], v[50:51]
	v_pk_mul_f32 v[48:49], v[130:131], v[178:179] op_sel_hi:[0,1]
	v_pk_mul_f32 v[50:51], v[130:131], v[180:181] op_sel_hi:[0,1]
	v_pk_fma_f32 v[90:91], v[196:197], v[50:51], v[78:79]
	v_pk_fma_f32 v[92:93], v[194:195], v[48:49], v[76:77]
	v_cvt_pk_bf16_f32 v49, v90, v91
	v_cvt_pk_bf16_f32 v48, v92, v93
	global_store_dwordx2 v[106:107], v[48:49], off
	v_pk_mul_f32 v[48:49], v[90:91], v[90:91]
	v_pk_mul_f32 v[50:51], v[92:93], v[92:93]
	s_nop 0
	v_pk_mov_b32 v[60:61], v[50:51], v[48:49] op_sel:[1,0]
	v_mov_b32_e32 v51, v49
	v_pk_add_f32 v[178:179], v[60:61], v[50:51]
	v_pk_mul_f32 v[48:49], v[232:233], v[236:237]
	v_mov_b32_e32 v60, v80
	v_mov_b32_e32 v61, v82
	v_mov_b32_e32 v82, v81
	v_pk_mul_f32 v[50:51], v[234:235], v[238:239]
	v_pk_mul_f32 v[60:61], v[128:129], v[60:61] op_sel_hi:[0,1]
	v_pk_mul_f32 v[62:63], v[128:129], v[82:83] op_sel_hi:[0,1]
	v_pk_fma_f32 v[76:77], v[62:63], v[50:51], v[42:43]
	v_pk_fma_f32 v[78:79], v[60:61], v[48:49], v[38:39]
	v_cvt_pk_bf16_f32 v39, v76, v77
	v_cvt_pk_bf16_f32 v38, v78, v79
	global_store_dwordx2 v[0:1], v[38:39], off offset:512
	v_pk_mul_f32 v[38:39], v[78:79], v[78:79]
	v_pk_mul_f32 v[42:43], v[76:77], v[76:77]
	s_nop 0
	v_pk_mov_b32 v[60:61], v[38:39], v[42:43] op_sel:[1,0]
	v_mov_b32_e32 v39, v43
	v_mov_b32_e32 v42, v84
	v_mov_b32_e32 v43, v86
	v_mov_b32_e32 v86, v85
	v_pk_add_f32 v[38:39], v[60:61], v[38:39]
	v_pk_mul_f32 v[42:43], v[120:121], v[42:43] op_sel_hi:[0,1]
	v_pk_mul_f32 v[60:61], v[120:121], v[86:87] op_sel_hi:[0,1]
	v_pk_fma_f32 v[80:81], v[60:61], v[50:51], v[58:59]
	v_pk_fma_f32 v[82:83], v[42:43], v[48:49], v[56:57]
	v_cvt_pk_bf16_f32 v43, v80, v81
	v_cvt_pk_bf16_f32 v42, v82, v83
	global_store_dwordx2 v[40:41], v[42:43], off offset:512
	v_pk_mul_f32 v[42:43], v[82:83], v[82:83]
	v_pk_mul_f32 v[56:57], v[80:81], v[80:81]
	s_nop 0
	v_pk_mov_b32 v[58:59], v[42:43], v[56:57] op_sel:[1,0]
	v_mov_b32_e32 v43, v57
	v_mov_b32_e32 v56, v162
	v_mov_b32_e32 v57, v164
	v_mov_b32_e32 v164, v163
	v_pk_add_f32 v[42:43], v[58:59], v[42:43]
	v_pk_mul_f32 v[56:57], v[146:147], v[56:57] op_sel_hi:[0,1]
	v_pk_mul_f32 v[58:59], v[146:147], v[164:165] op_sel_hi:[0,1]
	v_pk_fma_f32 v[84:85], v[58:59], v[50:51], v[68:69]
	v_pk_fma_f32 v[86:87], v[56:57], v[48:49], v[66:67]
	v_cvt_pk_bf16_f32 v57, v84, v85
	v_cvt_pk_bf16_f32 v56, v86, v87
	global_store_dwordx2 v[88:89], v[56:57], off offset:512
	v_pk_mul_f32 v[56:57], v[86:87], v[86:87]
	v_pk_mul_f32 v[58:59], v[84:85], v[84:85]
	s_nop 0
	v_pk_mov_b32 v[60:61], v[56:57], v[58:59] op_sel:[1,0]
	v_mov_b32_e32 v57, v59
	v_pk_add_f32 v[162:163], v[60:61], v[56:57]
	v_mov_b32_e32 v56, v166
	v_mov_b32_e32 v57, v172
	v_mov_b32_e32 v172, v167
	v_pk_mul_f32 v[56:57], v[130:131], v[56:57] op_sel_hi:[0,1]
	v_pk_mul_f32 v[58:59], v[130:131], v[172:173] op_sel_hi:[0,1]
	v_pk_fma_f32 v[72:73], v[50:51], v[58:59], v[124:125]
	v_pk_fma_f32 v[74:75], v[48:49], v[56:57], v[122:123]
	v_cvt_pk_bf16_f32 v49, v72, v73
	v_cvt_pk_bf16_f32 v48, v74, v75
	global_store_dwordx2 v[106:107], v[48:49], off offset:512
	v_pk_mul_f32 v[48:49], v[74:75], v[74:75]
	v_pk_mul_f32 v[50:51], v[72:73], v[72:73]
	s_nop 0
	v_pk_mov_b32 v[56:57], v[48:49], v[50:51] op_sel:[1,0]
	v_mov_b32_e32 v49, v51
	v_pk_add_f32 v[122:123], v[56:57], v[48:49]
	v_pk_mul_f32 v[50:51], v[242:243], v[246:247]
	v_pk_mul_f32 v[48:49], v[240:241], v[244:245]
	v_pk_mul_f32 v[56:57], v[128:129], v[132:133] op_sel_hi:[0,1]
	v_pk_mul_f32 v[58:59], v[128:129], v[134:135] op_sel_hi:[0,1]
	v_pk_fma_f32 v[60:61], v[58:59], v[50:51], v[36:37]
	v_pk_fma_f32 v[66:67], v[56:57], v[48:49], v[34:35]
	v_cvt_pk_bf16_f32 v35, v60, v61
	v_cvt_pk_bf16_f32 v34, v66, v67
	global_store_dwordx2 v[0:1], v[34:35], off offset:1024
	v_pk_mul_f32 v[34:35], v[120:121], v[136:137] op_sel_hi:[0,1]
	v_pk_mul_f32 v[36:37], v[120:121], v[138:139] op_sel_hi:[0,1]
	v_pk_fma_f32 v[62:63], v[36:37], v[50:51], v[54:55]
	v_pk_fma_f32 v[68:69], v[34:35], v[48:49], v[52:53]
	v_cvt_pk_bf16_f32 v35, v62, v63
	v_cvt_pk_bf16_f32 v34, v68, v69
	global_store_dwordx2 v[40:41], v[34:35], off offset:1024
	v_pk_mul_f32 v[34:35], v[146:147], v[154:155] op_sel_hi:[0,1]
	v_pk_mul_f32 v[36:37], v[146:147], v[156:157] op_sel_hi:[0,1]
	v_pk_fma_f32 v[64:65], v[36:37], v[50:51], v[64:65]
	v_pk_fma_f32 v[70:71], v[34:35], v[48:49], v[70:71]
	v_cvt_pk_bf16_f32 v35, v64, v65
	v_cvt_pk_bf16_f32 v34, v70, v71
	global_store_dwordx2 v[88:89], v[34:35], off offset:1024
	v_pk_mul_f32 v[34:35], v[130:131], v[158:159] op_sel_hi:[0,1]
	v_pk_mul_f32 v[36:37], v[130:131], v[160:161] op_sel_hi:[0,1]
	v_pk_fma_f32 v[56:57], v[36:37], v[50:51], v[114:115]
	v_pk_fma_f32 v[58:59], v[34:35], v[48:49], v[112:113]
	v_cvt_pk_bf16_f32 v35, v56, v57
	v_cvt_pk_bf16_f32 v34, v58, v59
	global_store_dwordx2 v[106:107], v[34:35], off offset:1024
	s_nop 0
	v_pk_mul_f32 v[50:51], v[214:215], v[218:219]
	v_pk_mul_f32 v[48:49], v[212:213], v[216:217]
	v_pk_mul_f32 v[34:35], v[128:129], v[118:119] op_sel_hi:[0,1]
	v_pk_mul_f32 v[36:37], v[128:129], v[116:117] op_sel_hi:[0,1]
	v_pk_fma_f32 v[32:33], v[36:37], v[50:51], v[32:33]
	v_pk_fma_f32 v[34:35], v[34:35], v[48:49], v[2:3]
	v_cvt_pk_bf16_f32 v3, v32, v33
	v_cvt_pk_bf16_f32 v2, v34, v35
	global_store_dwordx2 v[0:1], v[2:3], off offset:1536
	v_mul_f32_e32 v2, v34, v34
	v_pk_add_f32 v[0:1], v[198:199], v[198:199] op_sel:[0,1] op_sel_hi:[1,0]
	v_mul_f32_e32 v36, v35, v35
	v_mov_b32_e32 v1, v2
	v_pk_add_f32 v[2:3], v[38:39], v[38:39] op_sel:[0,1] op_sel_hi:[1,0]
	v_mul_f32_e32 v37, v32, v32
	v_mov_b32_e32 v3, v36
	v_pk_add_f32 v[0:1], v[0:1], v[2:3]
	v_mul_f32_e32 v2, v67, v67
	v_pk_fma_f32 v[2:3], v[66:67], v[66:67], v[2:3] op_sel_hi:[1,1,0]
	v_mul_f32_e32 v36, v61, v61
	v_mul_f32_e32 v52, v33, v33
	v_mov_b32_e32 v3, v37
	v_pk_fma_f32 v[36:37], v[60:61], v[60:61], v[36:37] op_sel_hi:[1,1,0]
	v_mov_b32_e32 v128, v131
	v_mov_b32_e32 v37, v52
	v_pk_add_f32 v[2:3], v[2:3], v[36:37]
	v_pk_mul_f32 v[36:37], v[120:121], v[126:127] op_sel_hi:[0,1]
	v_pk_add_f32 v[0:1], v[0:1], v[2:3]
	v_pk_mul_f32 v[2:3], v[120:121], v[128:129] op_sel_hi:[0,1]
	v_pk_fma_f32 v[36:37], v[36:37], v[50:51], v[46:47]
	v_pk_fma_f32 v[38:39], v[2:3], v[48:49], v[44:45]
	v_cvt_pk_bf16_f32 v3, v36, v37
	v_cvt_pk_bf16_f32 v2, v38, v39
	global_store_dwordx2 v[40:41], v[2:3], off offset:1536
	v_mul_f32_e32 v40, v38, v38
	v_pk_add_f32 v[2:3], v[200:201], v[200:201] op_sel:[0,1] op_sel_hi:[1,0]
	v_mul_f32_e32 v44, v39, v39
	v_mov_b32_e32 v3, v40
	v_pk_add_f32 v[40:41], v[42:43], v[42:43] op_sel:[0,1] op_sel_hi:[1,0]
	v_mul_f32_e32 v42, v63, v63
	v_mov_b32_e32 v41, v44
	v_pk_add_f32 v[2:3], v[2:3], v[40:41]
	v_mul_f32_e32 v40, v69, v69
	v_mul_f32_e32 v45, v36, v36
	v_mul_f32_e32 v46, v37, v37
	v_pk_fma_f32 v[40:41], v[68:69], v[68:69], v[40:41] op_sel_hi:[1,1,0]
	v_pk_fma_f32 v[42:43], v[62:63], v[62:63], v[42:43] op_sel_hi:[1,1,0]
	v_mov_b32_e32 v41, v45
	v_mov_b32_e32 v43, v46
	v_pk_add_f32 v[40:41], v[40:41], v[42:43]
	v_pk_mul_f32 v[42:43], v[146:147], v[144:145] op_sel_hi:[0,1]
	v_pk_add_f32 v[2:3], v[2:3], v[40:41]
	v_pk_mul_f32 v[40:41], v[146:147], v[142:143] op_sel_hi:[0,1]
	v_pk_fma_f32 v[40:41], v[40:41], v[50:51], v[104:105]
	v_pk_fma_f32 v[42:43], v[42:43], v[48:49], v[102:103]
	v_cvt_pk_bf16_f32 v45, v40, v41
	v_cvt_pk_bf16_f32 v44, v42, v43
	global_store_dwordx2 v[88:89], v[44:45], off offset:1536
	v_mul_f32_e32 v46, v42, v42
	v_pk_add_f32 v[44:45], v[176:177], v[176:177] op_sel:[0,1] op_sel_hi:[1,0]
	v_mul_f32_e32 v52, v43, v43
	v_mov_b32_e32 v45, v46
	v_pk_add_f32 v[46:47], v[162:163], v[162:163] op_sel:[0,1] op_sel_hi:[1,0]
	v_mul_f32_e32 v53, v40, v40
	v_mov_b32_e32 v47, v52
	v_pk_add_f32 v[44:45], v[44:45], v[46:47]
	v_mul_f32_e32 v46, v71, v71
	v_pk_fma_f32 v[46:47], v[70:71], v[70:71], v[46:47] op_sel_hi:[1,1,0]
	v_mul_f32_e32 v52, v65, v65
	v_mul_f32_e32 v54, v41, v41
	v_mov_b32_e32 v47, v53
	v_pk_fma_f32 v[52:53], v[64:65], v[64:65], v[52:53] op_sel_hi:[1,1,0]
	s_nop 0
	v_mov_b32_e32 v53, v54
	v_pk_add_f32 v[46:47], v[46:47], v[52:53]
	s_nop 0
	v_pk_add_f32 v[52:53], v[44:45], v[46:47]
	v_pk_mul_f32 v[46:47], v[130:131], v[150:151] op_sel_hi:[0,1]
	v_pk_mul_f32 v[44:45], v[130:131], v[148:149] op_sel_hi:[0,1]
	v_pk_fma_f32 v[44:45], v[44:45], v[50:51], v[110:111]
	v_pk_fma_f32 v[46:47], v[46:47], v[48:49], v[108:109]
	v_cvt_pk_bf16_f32 v49, v44, v45
	v_cvt_pk_bf16_f32 v48, v46, v47
	global_store_dwordx2 v[106:107], v[48:49], off offset:1536
	v_mul_f32_e32 v50, v46, v46
	v_pk_add_f32 v[48:49], v[178:179], v[178:179] op_sel:[0,1] op_sel_hi:[1,0]
	v_mul_f32_e32 v54, v47, v47
	v_mov_b32_e32 v49, v50
	v_pk_add_f32 v[50:51], v[122:123], v[122:123] op_sel:[0,1] op_sel_hi:[1,0]
	v_mul_f32_e32 v55, v44, v44
	v_mov_b32_e32 v51, v54
	v_pk_add_f32 v[48:49], v[48:49], v[50:51]
	v_mul_f32_e32 v50, v59, v59
	v_pk_fma_f32 v[50:51], v[58:59], v[58:59], v[50:51] op_sel_hi:[1,1,0]
	v_mul_f32_e32 v54, v57, v57
	v_mul_f32_e32 v88, v45, v45
	v_mov_b32_e32 v51, v55
	v_pk_fma_f32 v[54:55], v[56:57], v[56:57], v[54:55] op_sel_hi:[1,1,0]
	s_nop 0
	v_mov_b32_e32 v55, v88
	v_pk_add_f32 v[50:51], v[50:51], v[54:55]
	s_nop 0
	v_pk_add_f32 v[54:55], v[48:49], v[50:51]
	v_mov_b32_e32 v48, v2
	v_mov_b32_e32 v49, v0
	v_mov_b32_e32 v0, v3
	v_pk_add_f32 v[0:1], v[48:49], v[0:1]
	s_waitcnt lgkmcnt(0)
	s_waitcnt lgkmcnt(0)
	s_waitcnt lgkmcnt(0)
	s_waitcnt lgkmcnt(0)
	s_waitcnt lgkmcnt(0)
	s_waitcnt lgkmcnt(0)
	s_nop 1
	v_add_f32_dpp v0, v0, v0 row_ror:8 row_mask:0xf bank_mask:0xf
	v_add_f32_dpp v1, v1, v1 row_ror:8 row_mask:0xf bank_mask:0xf
	s_nop 0
	v_add_f32_dpp v0, v0, v0 row_ror:4 row_mask:0xf bank_mask:0xf
	v_add_f32_dpp v1, v1, v1 row_ror:4 row_mask:0xf bank_mask:0xf
	s_nop 0
	v_add_f32_dpp v0, v0, v0 row_ror:2 row_mask:0xf bank_mask:0xf
	v_add_f32_dpp v1, v1, v1 row_ror:2 row_mask:0xf bank_mask:0xf
	s_nop 0
	v_add_f32_dpp v0, v0, v0 row_ror:1 row_mask:0xf bank_mask:0xf
	v_add_f32_dpp v1, v1, v1 row_ror:1 row_mask:0xf bank_mask:0xf
	v_mov_b32_e32 v2, v0
	v_mov_b32_e32 v3, v1
	s_nop 1
	v_permlane16_swap_b32 v0, v2
	v_permlane16_swap_b32 v1, v3
	s_nop 1
	v_add_f32_e32 v0, v0, v2
	v_add_f32_e32 v1, v1, v3
	v_mov_b32_e32 v2, v0
	v_mov_b32_e32 v3, v1
	s_nop 1
	v_permlane32_swap_b32 v0, v2
	v_permlane32_swap_b32 v1, v3
	s_nop 1
	v_pk_add_f32 v[0:1], v[0:1], v[2:3]
	s_nop 0
	v_pk_fma_f32 v[0:1], v[0:1], s[6:7], v[140:141] op_sel_hi:[1,0,0]
	s_nop 0
	v_mul_f32_e32 v2, 0x4b800000, v1
	v_cmp_gt_f32_e64 s[0:1], s21, v1
	v_cmp_gt_f32_e32 vcc, s21, v0
	s_nop 0
	v_cndmask_b32_e64 v1, v1, v2, s[0:1]
	v_rsq_f32_e32 v1, v1
	s_nop 0
	v_mul_f32_e32 v2, 0x45800000, v1
	v_cndmask_b32_e64 v50, v1, v2, s[0:1]
	v_mul_f32_e32 v1, 0x4b800000, v0
	v_cndmask_b32_e32 v0, v0, v1, vcc
	v_rsq_f32_e32 v0, v0
	v_pk_mul_f32 v[78:79], v[78:79], v[50:51] op_sel_hi:[1,0]
	v_pk_mul_f32 v[76:77], v[76:77], v[50:51] op_sel_hi:[1,0]
	v_pk_mul_f32 v[66:67], v[66:67], v[50:51] op_sel_hi:[1,0]
	v_mul_f32_e32 v1, 0x45800000, v0
	v_cndmask_b32_e32 v48, v0, v1, vcc
	v_mov_b32_e32 v0, v54
	v_mov_b32_e32 v1, v52
	v_mov_b32_e32 v52, v55
	v_pk_add_f32 v[0:1], v[0:1], v[52:53]
	v_pk_mul_f32 v[96:97], v[96:97], v[48:49] op_sel_hi:[1,0]
	v_pk_mul_f32 v[94:95], v[94:95], v[48:49] op_sel_hi:[1,0]
	v_pk_mul_f32 v[60:61], v[60:61], v[50:51] op_sel_hi:[1,0]
	v_pk_mul_f32 v[62:63], v[62:63], v[48:49] op_sel_hi:[1,0]
	s_waitcnt lgkmcnt(0)
	v_pk_mul_f32 v[34:35], v[34:35], v[50:51] op_sel_hi:[1,0]
	v_pk_mul_f32 v[32:33], v[32:33], v[50:51] op_sel_hi:[1,0]
	s_waitcnt lgkmcnt(0)
	s_waitcnt lgkmcnt(0)
	s_waitcnt lgkmcnt(0)
	s_waitcnt lgkmcnt(0)
	s_waitcnt lgkmcnt(0)
	s_nop 1
	v_add_f32_dpp v0, v0, v0 row_ror:8 row_mask:0xf bank_mask:0xf
	v_add_f32_dpp v1, v1, v1 row_ror:8 row_mask:0xf bank_mask:0xf
	s_nop 0
	v_add_f32_dpp v0, v0, v0 row_ror:4 row_mask:0xf bank_mask:0xf
	v_add_f32_dpp v1, v1, v1 row_ror:4 row_mask:0xf bank_mask:0xf
	s_nop 0
	v_add_f32_dpp v0, v0, v0 row_ror:2 row_mask:0xf bank_mask:0xf
	v_add_f32_dpp v1, v1, v1 row_ror:2 row_mask:0xf bank_mask:0xf
	s_nop 0
	v_add_f32_dpp v0, v0, v0 row_ror:1 row_mask:0xf bank_mask:0xf
	v_add_f32_dpp v1, v1, v1 row_ror:1 row_mask:0xf bank_mask:0xf
	v_mov_b32_e32 v2, v0
	v_mov_b32_e32 v3, v1
	s_nop 1
	v_permlane16_swap_b32 v0, v2
	v_permlane16_swap_b32 v1, v3
	s_nop 1
	v_add_f32_e32 v0, v0, v2
	v_add_f32_e32 v1, v1, v3
	v_mov_b32_e32 v2, v0
	v_mov_b32_e32 v3, v1
	s_nop 1
	v_permlane32_swap_b32 v0, v2
	v_permlane32_swap_b32 v1, v3
	s_nop 1
	v_pk_add_f32 v[0:1], v[0:1], v[2:3]
	s_nop 0
	v_pk_fma_f32 v[0:1], v[0:1], s[6:7], v[140:141] op_sel_hi:[1,0,0]
	s_nop 0
	v_mul_f32_e32 v2, 0x4b800000, v1
	v_cmp_gt_f32_e64 s[0:1], s21, v1
	v_cmp_gt_f32_e32 vcc, s21, v0
	s_nop 0
	v_cndmask_b32_e64 v1, v1, v2, s[0:1]
	v_rsq_f32_e32 v1, v1
	s_nop 0
	v_mul_f32_e32 v2, 0x45800000, v1
	v_cndmask_b32_e64 v54, v1, v2, s[0:1]
	v_mul_f32_e32 v1, 0x4b800000, v0
	v_cndmask_b32_e32 v0, v0, v1, vcc
	v_rsq_f32_e32 v0, v0
	s_add_u32 s0, s5, 0x6000
	s_addc_u32 s1, s13, 0
	s_add_u32 s12, s5, 0x7000
	v_mul_f32_e32 v1, 0x45800000, v0
	v_cndmask_b32_e32 v52, v0, v1, vcc
	s_addc_u32 s13, s13, 0
	global_load_dwordx4 v[104:107], v[18:19], off
	global_load_dwordx4 v[108:111], v190, s[12:13]
	global_load_dwordx4 v[0:3], v190, s[0:1]
	v_pk_mul_f32 v[92:93], v[92:93], v[52:53] op_sel_hi:[1,0]
	v_pk_mul_f32 v[90:91], v[90:91], v[52:53] op_sel_hi:[1,0]
	s_or_b32 s16, s10, 0x1000
	v_pk_mul_f32 v[74:75], v[74:75], v[52:53] op_sel_hi:[1,0]
	v_pk_mul_f32 v[72:73], v[72:73], v[52:53] op_sel_hi:[1,0]
	v_pk_mul_f32 v[58:59], v[58:59], v[52:53] op_sel_hi:[1,0]
	v_pk_mul_f32 v[56:57], v[56:57], v[52:53] op_sel_hi:[1,0]
	s_add_i32 s2, s2, s3
	s_add_i32 s7, s7, s9
	s_add_i32 s18, s18, s19
	s_add_i32 s4, s4, s20
	s_waitcnt vmcnt(1)
	v_pk_add_f32 v[88:89], v[110:111], 1.0 op_sel_hi:[1,0]
	v_pk_add_f32 v[108:109], v[108:109], 1.0 op_sel_hi:[1,0]
	v_pk_mul_f32 v[102:103], v[106:107], v[88:89]
	v_pk_mul_f32 v[104:105], v[104:105], v[108:109]
	v_pk_mul_f32 v[88:89], v[182:183], v[50:51] op_sel_hi:[1,0]
	v_pk_mul_f32 v[106:107], v[174:175], v[50:51] op_sel_hi:[1,0]
	s_waitcnt vmcnt(0)
	v_pk_fma_f32 v[88:89], v[88:89], v[104:105], v[0:1]
	v_pk_fma_f32 v[94:95], v[94:95], v[102:103], v[2:3]
	v_pk_fma_f32 v[96:97], v[96:97], v[104:105], v[0:1]
	v_pk_fma_f32 v[108:109], v[106:107], v[102:103], v[2:3]
	v_cvt_pk_bf16_f32 v106, v88, v89
	v_lshl_add_u64 v[88:89], v[8:9], 0, s[10:11]
	v_cvt_pk_bf16_f32 v96, v96, v97
	v_cvt_pk_bf16_f32 v97, v94, v95
	global_store_dwordx2 v[88:89], v[96:97], off offset:2048
	v_pk_mul_f32 v[94:95], v[100:101], v[54:55] op_sel_hi:[1,0]
	v_pk_mul_f32 v[96:97], v[98:99], v[54:55] op_sel_hi:[1,0]
	v_pk_fma_f32 v[94:95], v[104:105], v[94:95], v[0:1]
	v_pk_fma_f32 v[96:97], v[102:103], v[96:97], v[2:3]
	v_pk_fma_f32 v[2:3], v[102:103], v[90:91], v[2:3]
	v_pk_fma_f32 v[0:1], v[104:105], v[92:93], v[0:1]
	s_or_b32 s10, s10, 0x1800
	v_cvt_pk_bf16_f32 v107, v108, v109
	v_cvt_pk_bf16_f32 v94, v94, v95
	v_cvt_pk_bf16_f32 v95, v96, v97
	v_lshl_add_u64 v[96:97], v[8:9], 0, s[16:17]
	v_cvt_pk_bf16_f32 v0, v0, v1
	v_cvt_pk_bf16_f32 v1, v2, v3
	v_lshl_add_u64 v[2:3], v[8:9], 0, s[10:11]
	global_store_dwordx2 v[88:89], v[106:107], off
	global_store_dwordx2 v[96:97], v[94:95], off
	global_store_dwordx2 v[2:3], v[0:1], off
	global_load_dwordx4 v[0:3], v[20:21], off
	s_nop 0
	global_load_dwordx4 v[90:93], v191, s[12:13]
	global_load_dwordx4 v[94:97], v191, s[0:1]
	s_cmpk_lt_i32 s2, 0x4000
	s_waitcnt vmcnt(1)
	v_pk_add_f32 v[92:93], v[92:93], 1.0 op_sel_hi:[1,0]
	v_pk_add_f32 v[90:91], v[90:91], 1.0 op_sel_hi:[1,0]
	v_pk_mul_f32 v[2:3], v[2:3], v[92:93]
	v_pk_mul_f32 v[0:1], v[0:1], v[90:91]
	s_waitcnt vmcnt(0)
	v_pk_fma_f32 v[76:77], v[76:77], v[2:3], v[96:97]
	v_pk_fma_f32 v[78:79], v[78:79], v[0:1], v[94:95]
	s_nop 0
	v_cvt_pk_bf16_f32 v78, v78, v79
	v_cvt_pk_bf16_f32 v79, v76, v77
	global_store_dwordx2 v[88:89], v[78:79], off offset:512
	v_pk_mul_f32 v[76:77], v[82:83], v[48:49] op_sel_hi:[1,0]
	v_pk_mul_f32 v[78:79], v[80:81], v[48:49] op_sel_hi:[1,0]
	v_pk_fma_f32 v[76:77], v[76:77], v[0:1], v[94:95]
	v_pk_fma_f32 v[78:79], v[78:79], v[2:3], v[96:97]
	v_cvt_pk_bf16_f32 v76, v76, v77
	v_cvt_pk_bf16_f32 v77, v78, v79
	global_store_dwordx2 v[88:89], v[76:77], off offset:2560
	v_pk_mul_f32 v[76:77], v[86:87], v[54:55] op_sel_hi:[1,0]
	v_pk_mul_f32 v[78:79], v[84:85], v[54:55] op_sel_hi:[1,0]
	v_pk_fma_f32 v[76:77], v[76:77], v[0:1], v[94:95]
	v_pk_fma_f32 v[78:79], v[78:79], v[2:3], v[96:97]
	v_pk_fma_f32 v[2:3], v[2:3], v[72:73], v[96:97]
	v_pk_fma_f32 v[0:1], v[0:1], v[74:75], v[94:95]
	v_cvt_pk_bf16_f32 v76, v76, v77
	v_cvt_pk_bf16_f32 v77, v78, v79
	v_lshl_add_u64 v[78:79], v[22:23], 0, s[16:17]
	v_cvt_pk_bf16_f32 v0, v0, v1
	v_cvt_pk_bf16_f32 v1, v2, v3
	v_lshl_add_u64 v[2:3], v[22:23], 0, s[10:11]
	global_store_dwordx2 v[78:79], v[76:77], off
	global_store_dwordx2 v[2:3], v[0:1], off
	global_load_dwordx4 v[0:3], v[24:25], off
	s_nop 0
	global_load_dwordx4 v[72:75], v192, s[12:13]
	global_load_dwordx4 v[76:79], v192, s[0:1]
	s_waitcnt vmcnt(1)
	v_pk_add_f32 v[74:75], v[74:75], 1.0 op_sel_hi:[1,0]
	v_pk_add_f32 v[72:73], v[72:73], 1.0 op_sel_hi:[1,0]
	v_pk_mul_f32 v[2:3], v[2:3], v[74:75]
	v_pk_mul_f32 v[0:1], v[0:1], v[72:73]
	s_waitcnt vmcnt(0)
	v_pk_fma_f32 v[60:61], v[60:61], v[2:3], v[78:79]
	v_pk_fma_f32 v[66:67], v[66:67], v[0:1], v[76:77]
	v_pk_fma_f32 v[62:63], v[62:63], v[2:3], v[78:79]
	v_cvt_pk_bf16_f32 v66, v66, v67
	v_cvt_pk_bf16_f32 v67, v60, v61
	v_pk_mul_f32 v[60:61], v[68:69], v[48:49] op_sel_hi:[1,0]
	global_store_dwordx2 v[88:89], v[66:67], off offset:1024
	v_pk_fma_f32 v[60:61], v[60:61], v[0:1], v[76:77]
	s_nop 0
	v_cvt_pk_bf16_f32 v60, v60, v61
	v_cvt_pk_bf16_f32 v61, v62, v63
	global_store_dwordx2 v[88:89], v[60:61], off offset:3072
	v_pk_mul_f32 v[60:61], v[70:71], v[54:55] op_sel_hi:[1,0]
	v_pk_mul_f32 v[62:63], v[64:65], v[54:55] op_sel_hi:[1,0]
	v_pk_fma_f32 v[60:61], v[60:61], v[0:1], v[76:77]
	v_pk_fma_f32 v[62:63], v[62:63], v[2:3], v[78:79]
	v_pk_fma_f32 v[2:3], v[56:57], v[2:3], v[78:79]
	v_pk_fma_f32 v[0:1], v[58:59], v[0:1], v[76:77]
	v_cvt_pk_bf16_f32 v60, v60, v61
	v_cvt_pk_bf16_f32 v61, v62, v63
	v_lshl_add_u64 v[62:63], v[26:27], 0, s[16:17]
	v_cvt_pk_bf16_f32 v0, v0, v1
	v_cvt_pk_bf16_f32 v1, v2, v3
	v_lshl_add_u64 v[2:3], v[26:27], 0, s[10:11]
	global_store_dwordx2 v[62:63], v[60:61], off
	global_store_dwordx2 v[2:3], v[0:1], off
	global_load_dwordx4 v[0:3], v[28:29], off
	s_nop 0
	global_load_dwordx4 v[56:59], v193, s[12:13]
	global_load_dwordx4 v[60:63], v193, s[0:1]
	s_waitcnt vmcnt(1)
	v_pk_add_f32 v[58:59], v[58:59], 1.0 op_sel_hi:[1,0]
	v_pk_add_f32 v[56:57], v[56:57], 1.0 op_sel_hi:[1,0]
	v_pk_mul_f32 v[2:3], v[2:3], v[58:59]
	v_pk_mul_f32 v[0:1], v[0:1], v[56:57]
	s_waitcnt vmcnt(0)
	v_pk_fma_f32 v[32:33], v[32:33], v[2:3], v[62:63]
	v_pk_fma_f32 v[34:35], v[34:35], v[0:1], v[60:61]
	s_nop 0
	v_cvt_pk_bf16_f32 v34, v34, v35
	v_cvt_pk_bf16_f32 v35, v32, v33
	global_store_dwordx2 v[88:89], v[34:35], off offset:1536
	v_pk_mul_f32 v[32:33], v[38:39], v[48:49] op_sel_hi:[1,0]
	v_pk_mul_f32 v[34:35], v[36:37], v[48:49] op_sel_hi:[1,0]
	v_pk_fma_f32 v[32:33], v[32:33], v[0:1], v[60:61]
	v_pk_fma_f32 v[34:35], v[34:35], v[2:3], v[62:63]
	v_cvt_pk_bf16_f32 v32, v32, v33
	v_cvt_pk_bf16_f32 v33, v34, v35
	global_store_dwordx2 v[88:89], v[32:33], off offset:3584
	v_pk_mul_f32 v[32:33], v[42:43], v[54:55] op_sel_hi:[1,0]
	v_pk_mul_f32 v[34:35], v[40:41], v[54:55] op_sel_hi:[1,0]
	v_pk_fma_f32 v[32:33], v[32:33], v[0:1], v[60:61]
	v_pk_fma_f32 v[34:35], v[34:35], v[2:3], v[62:63]
	v_cvt_pk_bf16_f32 v32, v32, v33
	v_cvt_pk_bf16_f32 v33, v34, v35
	v_lshl_add_u64 v[34:35], v[30:31], 0, s[16:17]
	global_store_dwordx2 v[34:35], v[32:33], off
	v_pk_mul_f32 v[32:33], v[46:47], v[52:53] op_sel_hi:[1,0]
	v_pk_mul_f32 v[34:35], v[44:45], v[52:53] op_sel_hi:[1,0]
	v_pk_fma_f32 v[0:1], v[32:33], v[0:1], v[60:61]
	v_pk_fma_f32 v[2:3], v[34:35], v[2:3], v[62:63]
	v_cvt_pk_bf16_f32 v0, v0, v1
	v_cvt_pk_bf16_f32 v1, v2, v3
	v_lshl_add_u64 v[2:3], v[30:31], 0, s[10:11]
	global_store_dwordx2 v[2:3], v[0:1], off
	s_cbranch_scc1 .LBB0_912

.LBB0_1103:
	s_ashr_i32 s7, s6, 31
	s_add_i32 s0, s6, 1
	s_ashr_i32 s16, s9, 11
	s_add_i32 s2, s6, 2
	s_add_i32 s4, s6, 3
	s_lshl_b64 s[10:11], s[6:7], 11
	s_ashr_i32 s1, s0, 31
	s_mul_i32 s16, s16, 9
	s_ashr_i32 s3, s2, 31
	s_ashr_i32 s5, s4, 31
	v_lshl_add_u64 v[22:23], v[4:5], 0, s[10:11]
	v_lshl_add_u64 v[24:25], v[6:7], 0, s[10:11]
	s_lshl_b64 s[10:11], s[0:1], 11
	s_ashr_i32 s17, s16, 31
	global_load_dwordx4 v[0:3], v[10:11], off
	s_lshl_b64 s[18:19], s[2:3], 11
	s_lshl_b64 s[20:21], s[4:5], 11
	global_load_dwordx2 v[36:37], v[24:25], off
	global_load_dwordx2 v[38:39], v[22:23], off
	global_load_dwordx2 v[40:41], v[22:23], off offset:512
	global_load_dwordx2 v[42:43], v[22:23], off offset:1024
	global_load_dwordx2 v[44:45], v[22:23], off offset:1536
	global_load_dwordx2 v[46:47], v[22:23], off offset:2048
	global_load_dwordx2 v[50:51], v[22:23], off offset:2560
	global_load_dwordx2 v[76:77], v[24:25], off offset:512
	global_load_dwordx2 v[48:49], v[24:25], off offset:1024
	global_load_dwordx2 v[20:21], v[24:25], off offset:1536
	v_lshl_add_u64 v[26:27], v[6:7], 0, s[10:11]
	global_load_dwordx2 v[52:53], v[22:23], off offset:3072
	global_load_dwordx2 v[54:55], v[22:23], off offset:3584
	s_lshl_b64 s[10:11], s[16:17], 12
	s_add_u32 s10, s88, s10
	v_add_co_u32_e32 v30, vcc, s14, v22
	s_addc_u32 s11, s89, s11
	v_lshl_add_u64 v[28:29], v[6:7], 0, s[18:19]
	v_addc_co_u32_e32 v31, vcc, 0, v23, vcc
	v_lshl_add_u64 v[32:33], v[6:7], 0, s[20:21]
	global_load_dwordx2 v[60:61], v[26:27], off
	global_load_dwordx2 v[62:63], v[28:29], off
	global_load_dwordx2 v[66:67], v[32:33], off
	global_load_dwordx2 v[78:79], v[26:27], off offset:512
	global_load_dwordx2 v[56:57], v[26:27], off offset:1024
	global_load_dwordx2 v[22:23], v[26:27], off offset:1536
	global_load_dwordx2 v[84:85], v[30:31], off
	global_load_dwordx2 v[86:87], v[30:31], off offset:512
	global_load_dwordx2 v[88:89], v[30:31], off offset:1024
	global_load_dwordx2 v[90:91], v[30:31], off offset:1536
	global_load_dwordx2 v[80:81], v[28:29], off offset:512
	global_load_dwordx2 v[58:59], v[28:29], off offset:1024
	global_load_dwordx2 v[24:25], v[28:29], off offset:1536
	global_load_dwordx2 v[104:105], v[30:31], off offset:2048
	global_load_dwordx2 v[106:107], v[30:31], off offset:2560
	global_load_dwordx2 v[130:131], v[30:31], off offset:3072
	global_load_dwordx2 v[132:133], v[30:31], off offset:3584
	global_load_dwordx2 v[82:83], v[32:33], off offset:512
	global_load_dwordx2 v[64:65], v[32:33], off offset:1024
	global_load_dwordx2 v[26:27], v[32:33], off offset:1536
	s_add_u32 s10, s10, 0x8000
	s_addc_u32 s11, s11, 0
	global_load_dwordx4 v[126:129], v122, s[10:11]
	s_lshl_b64 s[0:1], s[0:1], 12
	s_lshl_b64 s[4:5], s[4:5], 12
	v_lshl_add_u64 v[30:31], v[8:9], 0, s[0:1]
	s_lshl_b64 s[2:3], s[2:3], 12
	v_lshl_add_u64 v[34:35], v[8:9], 0, s[4:5]
	v_lshl_add_u64 v[32:33], v[8:9], 0, s[2:3]
	s_lshl_b64 s[16:17], s[6:7], 12
	v_lshl_add_u64 v[28:29], v[8:9], 0, s[16:17]
	s_add_i32 s6, s6, s13
	global_load_dwordx4 v[220:223], v123, s[10:11]
	global_load_dwordx4 v[224:227], v[12:13], off
	global_load_dwordx4 v[228:231], v124, s[10:11]
	global_load_dwordx4 v[232:235], v[14:15], off
	global_load_dwordx4 v[236:239], v125, s[10:11]
	global_load_dwordx4 v[240:243], v[16:17], off
	s_waitcnt vmcnt(26)
	v_lshlrev_b32_e32 v138, 16, v60
	v_and_b32_e32 v113, 0xffff0000, v38
	v_and_b32_e32 v115, 0xffff0000, v39
	v_and_b32_e32 v97, 0xffff0000, v41
	v_and_b32_e32 v96, 0xffff0000, v40
	v_and_b32_e32 v69, 0xffff0000, v42
	v_and_b32_e32 v135, 0xffff0000, v46
	v_and_b32_e32 v137, 0xffff0000, v47
	v_lshlrev_b32_e32 v108, 16, v36
	v_and_b32_e32 v109, 0xffff0000, v36
	v_and_b32_e32 v71, 0xffff0000, v52
	v_and_b32_e32 v75, 0xffff0000, v53
	v_lshlrev_b32_e32 v110, 16, v37
	v_and_b32_e32 v111, 0xffff0000, v37
	v_lshlrev_b32_e32 v112, 16, v38
	v_lshlrev_b32_e32 v114, 16, v39
	v_lshlrev_b32_e32 v93, 16, v41
	v_lshlrev_b32_e32 v92, 16, v40
	v_lshlrev_b32_e32 v68, 16, v42
	v_lshlrev_b32_e32 v72, 16, v43
	v_and_b32_e32 v73, 0xffff0000, v43
	v_lshlrev_b32_e32 v41, 16, v44
	v_and_b32_e32 v37, 0xffff0000, v44
	v_lshlrev_b32_e32 v38, 16, v45
	v_and_b32_e32 v39, 0xffff0000, v45
	v_lshlrev_b32_e32 v134, 16, v46
	v_lshlrev_b32_e32 v136, 16, v47
	v_lshlrev_b32_e32 v95, 16, v51
	v_lshlrev_b32_e32 v94, 16, v50
	v_and_b32_e32 v99, 0xffff0000, v51
	v_and_b32_e32 v98, 0xffff0000, v50
	v_lshlrev_b32_e32 v70, 16, v52
	v_lshlrev_b32_e32 v74, 16, v53
	v_lshlrev_b32_e32 v47, 16, v54
	v_and_b32_e32 v43, 0xffff0000, v54
	v_lshlrev_b32_e32 v44, 16, v55
	v_and_b32_e32 v45, 0xffff0000, v55
	v_and_b32_e32 v139, 0xffff0000, v60
	v_lshlrev_b32_e32 v140, 16, v61
	v_and_b32_e32 v141, 0xffff0000, v61
	s_waitcnt vmcnt(24)
	v_lshlrev_b32_e32 v146, 16, v66
	v_and_b32_e32 v147, 0xffff0000, v66
	v_lshlrev_b32_e32 v148, 16, v67
	v_and_b32_e32 v149, 0xffff0000, v67
	v_mul_f32_e32 v36, v115, v115
	v_pk_mul_f32 v[150:151], v[96:97], v[96:97]
	v_mul_f32_e32 v40, v113, v113
	v_mul_f32_e32 v42, v69, v69
	v_mul_f32_e32 v50, v137, v137
	v_mul_f32_e32 v54, v135, v135
	v_mul_f32_e32 v60, v71, v71
	v_mul_f32_e32 v66, v75, v75
	s_waitcnt vmcnt(20)
	v_and_b32_e32 v159, 0xffff0000, v84
	v_and_b32_e32 v161, 0xffff0000, v85
	s_waitcnt vmcnt(19)
	v_and_b32_e32 v103, 0xffff0000, v87
	v_and_b32_e32 v102, 0xffff0000, v86
	s_waitcnt vmcnt(17)
	v_lshlrev_b32_e32 v55, 16, v90
	v_and_b32_e32 v51, 0xffff0000, v90
	s_waitcnt vmcnt(13)
	v_and_b32_e32 v163, 0xffff0000, v104
	v_and_b32_e32 v165, 0xffff0000, v105
	s_waitcnt vmcnt(10)
	v_lshlrev_b32_e32 v67, 16, v132
	v_and_b32_e32 v61, 0xffff0000, v132
	v_lshlrev_b32_e32 v142, 16, v62
	v_and_b32_e32 v143, 0xffff0000, v62
	v_lshlrev_b32_e32 v144, 16, v63
	v_and_b32_e32 v145, 0xffff0000, v63
	v_mul_f32_e32 v156, v38, v38
	v_mul_f32_e32 v46, v73, v73
	v_pk_mul_f32 v[154:155], v[98:99], v[98:99]
	v_lshlrev_b32_e32 v158, 16, v84
	v_lshlrev_b32_e32 v160, 16, v85
	v_lshlrev_b32_e32 v101, 16, v87
	v_lshlrev_b32_e32 v100, 16, v86
	v_lshlrev_b32_e32 v84, 16, v88
	v_and_b32_e32 v85, 0xffff0000, v88
	v_lshlrev_b32_e32 v88, 16, v89
	v_and_b32_e32 v89, 0xffff0000, v89
	v_lshlrev_b32_e32 v52, 16, v91
	v_and_b32_e32 v53, 0xffff0000, v91
	v_lshlrev_b32_e32 v162, 16, v104
	v_lshlrev_b32_e32 v164, 16, v105
	v_lshlrev_b32_e32 v105, 16, v107
	v_lshlrev_b32_e32 v104, 16, v106
	v_and_b32_e32 v107, 0xffff0000, v107
	v_and_b32_e32 v106, 0xffff0000, v106
	v_lshlrev_b32_e32 v86, 16, v130
	v_and_b32_e32 v87, 0xffff0000, v130
	v_lshlrev_b32_e32 v90, 16, v131
	v_and_b32_e32 v91, 0xffff0000, v131
	v_lshlrev_b32_e32 v62, 16, v133
	v_and_b32_e32 v63, 0xffff0000, v133
	v_pk_fma_f32 v[130:131], v[114:115], v[114:115], v[36:37] op_sel_hi:[1,1,0]
	v_pk_fma_f32 v[132:133], v[92:93], v[92:93], v[150:151]
	v_pk_fma_f32 v[150:151], v[112:113], v[112:113], v[40:41] op_sel_hi:[1,1,0]
	v_pk_fma_f32 v[166:167], v[68:69], v[68:69], v[42:43] op_sel_hi:[1,1,0]
	v_pk_fma_f32 v[170:171], v[136:137], v[136:137], v[50:51] op_sel_hi:[1,1,0]
	v_pk_fma_f32 v[172:173], v[134:135], v[134:135], v[54:55] op_sel_hi:[1,1,0]
	v_pk_fma_f32 v[174:175], v[70:71], v[70:71], v[60:61] op_sel_hi:[1,1,0]
	v_pk_fma_f32 v[176:177], v[74:75], v[74:75], v[66:67] op_sel_hi:[1,1,0]
	v_mul_f32_e32 v36, v161, v161
	v_pk_mul_f32 v[178:179], v[102:103], v[102:103]
	v_mul_f32_e32 v42, v159, v159
	v_mul_f32_e32 v60, v165, v165
	v_mul_f32_e32 v66, v163, v163
	v_mul_f32_e32 v186, v39, v39
	v_mov_b32_e32 v153, v41
	v_mul_f32_e32 v187, v44, v44
	v_mul_f32_e32 v188, v45, v45
	v_mov_b32_e32 v157, v47
	v_pk_fma_f32 v[168:169], v[72:73], v[72:73], v[46:47] op_sel_hi:[1,1,0]
	v_pk_fma_f32 v[154:155], v[94:95], v[94:95], v[154:155]
	v_mov_b32_e32 v181, v55
	v_mul_f32_e32 v54, v89, v89
	v_pk_mul_f32 v[182:183], v[106:107], v[106:107]
	v_mov_b32_e32 v185, v67
	v_mul_f32_e32 v180, v87, v87
	v_mul_f32_e32 v184, v91, v91
	v_mov_b32_e32 v40, v150
	v_mov_b32_e32 v152, v130
	v_pk_add_f32 v[130:131], v[150:151], v[130:131]
	v_mov_b32_e32 v167, v156
	v_mov_b32_e32 v46, v172
	v_mov_b32_e32 v156, v170
	v_pk_add_f32 v[150:151], v[172:173], v[170:171]
	v_pk_fma_f32 v[170:171], v[160:161], v[160:161], v[36:37] op_sel_hi:[1,1,0]
	v_pk_fma_f32 v[172:173], v[100:101], v[100:101], v[178:179]
	v_pk_fma_f32 v[178:179], v[158:159], v[158:159], v[42:43] op_sel_hi:[1,1,0]
	v_pk_fma_f32 v[190:191], v[164:165], v[164:165], v[60:61] op_sel_hi:[1,1,0]
	v_pk_fma_f32 v[192:193], v[162:163], v[162:163], v[66:67] op_sel_hi:[1,1,0]
	v_mul_f32_e32 v198, v37, v37
	v_mul_f32_e32 v199, v43, v43
	v_mul_f32_e32 v50, v85, v85
	v_pk_add_f32 v[132:133], v[132:133], v[132:133] op_sel:[0,1] op_sel_hi:[1,0]
	v_mov_b32_e32 v169, v186
	v_pk_add_f32 v[154:155], v[154:155], v[154:155] op_sel:[0,1] op_sel_hi:[1,0]
	v_mov_b32_e32 v175, v187
	v_mov_b32_e32 v177, v188
	v_pk_fma_f32 v[188:189], v[88:89], v[88:89], v[54:55] op_sel_hi:[1,1,0]
	v_pk_fma_f32 v[182:183], v[104:105], v[104:105], v[182:183]
	v_pk_fma_f32 v[194:195], v[86:87], v[86:87], v[180:181] op_sel_hi:[1,1,0]
	v_pk_fma_f32 v[196:197], v[90:91], v[90:91], v[184:185] op_sel_hi:[1,1,0]
	v_pk_mul_f32 v[152:153], v[40:41], v[152:153]
	v_pk_mul_f32 v[156:157], v[46:47], v[156:157]
	v_mov_b32_e32 v54, v178
	v_mov_b32_e32 v180, v170
	v_mov_b32_e32 v66, v192
	v_mov_b32_e32 v184, v190
	v_mul_f32_e32 v200, v51, v51
	v_mul_f32_e32 v201, v52, v52
	v_mul_f32_e32 v202, v53, v53
	v_mul_f32_e32 v203, v61, v61
	v_mul_f32_e32 v204, v62, v62
	v_mul_f32_e32 v205, v63, v63
	v_pk_fma_f32 v[186:187], v[84:85], v[84:85], v[50:51] op_sel_hi:[1,1,0]
	v_mov_b32_e32 v133, v198
	v_pk_add_f32 v[166:167], v[166:167], v[168:169]
	v_mov_b32_e32 v155, v199
	v_pk_add_f32 v[168:169], v[174:175], v[176:177]
	v_pk_add_f32 v[170:171], v[178:179], v[170:171]
	v_pk_add_f32 v[172:173], v[172:173], v[172:173] op_sel:[0,1] op_sel_hi:[1,0]
	v_pk_add_f32 v[174:175], v[192:193], v[190:191]
	v_pk_add_f32 v[176:177], v[182:183], v[182:183] op_sel:[0,1] op_sel_hi:[1,0]
	v_mov_b32_e32 v131, v153
	v_mov_b32_e32 v151, v157
	v_pk_mul_f32 v[152:153], v[54:55], v[180:181]
	v_pk_mul_f32 v[178:179], v[66:67], v[184:185]
	v_mov_b32_e32 v187, v201
	v_mov_b32_e32 v189, v202
	v_mov_b32_e32 v195, v204
	v_mov_b32_e32 v197, v205
	v_mov_b32_e32 v173, v200
	v_mov_b32_e32 v177, v203
	s_waitcnt vmcnt(0)
	v_pk_mul_f32 v[128:129], v[128:129], v[2:3]
	v_pk_mul_f32 v[126:127], v[126:127], v[0:1]
	v_pk_add_f32 v[0:1], v[130:131], v[132:133]
	v_pk_add_f32 v[2:3], v[150:151], v[154:155]
	v_mov_b32_e32 v171, v153
	v_mov_b32_e32 v175, v179
	v_pk_add_f32 v[156:157], v[186:187], v[188:189]
	v_pk_add_f32 v[180:181], v[194:195], v[196:197]
	v_pk_add_f32 v[0:1], v[0:1], v[166:167]
	v_pk_add_f32 v[2:3], v[2:3], v[168:169]
	v_pk_add_f32 v[130:131], v[170:171], v[172:173]
	v_pk_add_f32 v[132:133], v[174:175], v[176:177]
	v_mov_b32_e32 v150, v2
	v_mov_b32_e32 v151, v0
	v_mov_b32_e32 v0, v3
	v_pk_add_f32 v[2:3], v[130:131], v[156:157]
	v_pk_add_f32 v[130:131], v[132:133], v[180:181]
	v_pk_add_f32 v[0:1], v[150:151], v[0:1]
	v_mov_b32_e32 v132, v130
	v_mov_b32_e32 v133, v2
	v_mov_b32_e32 v2, v131
	v_pk_add_f32 v[2:3], v[132:133], v[2:3]
	v_mov_b32_e32 v50, v55
	s_waitcnt lgkmcnt(2)
	s_waitcnt lgkmcnt(2)
	v_mov_b32_e32 v60, v67
	s_waitcnt lgkmcnt(2)
	s_waitcnt lgkmcnt(2)
	s_waitcnt lgkmcnt(2)
	s_waitcnt lgkmcnt(2)
	s_waitcnt lgkmcnt(2)
	s_waitcnt lgkmcnt(2)
	s_waitcnt lgkmcnt(2)
	s_waitcnt lgkmcnt(2)
	s_waitcnt lgkmcnt(2)
	s_nop 1
	v_add_f32_dpp v0, v0, v0 row_ror:8 row_mask:0xf bank_mask:0xf
	v_add_f32_dpp v1, v1, v1 row_ror:8 row_mask:0xf bank_mask:0xf
	s_nop 0
	v_add_f32_dpp v0, v0, v0 row_ror:4 row_mask:0xf bank_mask:0xf
	v_add_f32_dpp v1, v1, v1 row_ror:4 row_mask:0xf bank_mask:0xf
	s_nop 0
	v_add_f32_dpp v0, v0, v0 row_ror:2 row_mask:0xf bank_mask:0xf
	v_add_f32_dpp v1, v1, v1 row_ror:2 row_mask:0xf bank_mask:0xf
	s_nop 0
	v_add_f32_dpp v0, v0, v0 row_ror:1 row_mask:0xf bank_mask:0xf
	v_add_f32_dpp v1, v1, v1 row_ror:1 row_mask:0xf bank_mask:0xf
	v_mov_b32_e32 v130, v0
	v_mov_b32_e32 v131, v1
	s_nop 1
	v_permlane16_swap_b32 v0, v130
	v_permlane16_swap_b32 v1, v131
	s_nop 1
	v_add_f32_e32 v0, v0, v130
	v_add_f32_e32 v1, v1, v131
	v_mov_b32_e32 v130, v0
	v_mov_b32_e32 v131, v1
	s_nop 1
	v_permlane32_swap_b32 v0, v130
	v_permlane32_swap_b32 v1, v131
	s_nop 1
	v_pk_add_f32 v[0:1], v[0:1], v[130:131]
	s_nop 0
	v_pk_fma_f32 v[0:1], v[0:1], s[8:9], v[18:19] op_sel_hi:[1,0,0]
	s_waitcnt lgkmcnt(0)
	s_nop 1
	v_add_f32_dpp v2, v2, v2 row_ror:8 row_mask:0xf bank_mask:0xf
	v_add_f32_dpp v3, v3, v3 row_ror:8 row_mask:0xf bank_mask:0xf
	s_nop 0
	v_add_f32_dpp v2, v2, v2 row_ror:4 row_mask:0xf bank_mask:0xf
	v_add_f32_dpp v3, v3, v3 row_ror:4 row_mask:0xf bank_mask:0xf
	s_nop 0
	v_add_f32_dpp v2, v2, v2 row_ror:2 row_mask:0xf bank_mask:0xf
	v_add_f32_dpp v3, v3, v3 row_ror:2 row_mask:0xf bank_mask:0xf
	s_nop 0
	v_add_f32_dpp v2, v2, v2 row_ror:1 row_mask:0xf bank_mask:0xf
	v_add_f32_dpp v3, v3, v3 row_ror:1 row_mask:0xf bank_mask:0xf
	v_mov_b32_e32 v132, v2
	v_mov_b32_e32 v133, v3
	s_nop 1
	v_permlane16_swap_b32 v2, v132
	v_permlane16_swap_b32 v3, v133
	s_nop 1
	v_add_f32_e32 v2, v2, v132
	v_add_f32_e32 v3, v3, v133
	v_mov_b32_e32 v132, v2
	v_mov_b32_e32 v133, v3
	s_nop 1
	v_permlane32_swap_b32 v2, v132
	v_permlane32_swap_b32 v3, v133
	s_nop 1
	v_pk_add_f32 v[2:3], v[2:3], v[132:133]
	v_mul_f32_e32 v36, 0x4b800000, v1
	v_mul_f32_e32 v40, 0x4b800000, v0
	v_cmp_gt_f32_e32 vcc, s15, v0
	v_pk_fma_f32 v[2:3], v[2:3], s[8:9], v[18:19] op_sel_hi:[1,0,0]
	v_cmp_gt_f32_e64 s[0:1], s15, v1
	v_cndmask_b32_e32 v0, v0, v40, vcc
	v_cmp_gt_f32_e64 s[4:5], s15, v3
	v_cndmask_b32_e64 v1, v1, v36, s[0:1]
	v_mul_f32_e32 v36, 0x4b800000, v3
	v_mul_f32_e32 v40, 0x4b800000, v2
	v_cmp_gt_f32_e64 s[2:3], s15, v2
	v_rsq_f32_e32 v1, v1
	v_rsq_f32_e32 v0, v0
	v_cndmask_b32_e64 v3, v3, v36, s[4:5]
	v_cndmask_b32_e64 v2, v2, v40, s[2:3]
	v_rsq_f32_e32 v3, v3
	v_rsq_f32_e32 v2, v2
	v_mul_f32_e32 v36, 0x45800000, v1
	v_mul_f32_e32 v40, 0x45800000, v0
	v_cndmask_b32_e64 v1, v1, v36, s[0:1]
	v_cndmask_b32_e32 v0, v0, v40, vcc
	v_mul_f32_e32 v36, 0x45800000, v3
	v_mul_f32_e32 v42, 0x45800000, v2
	v_mul_f32_e32 v40, 0.5, v1
	v_mul_f32_e32 v0, 0.5, v0
	v_cndmask_b32_e64 v1, v3, v36, s[4:5]
	v_cndmask_b32_e64 v2, v2, v42, s[2:3]
	v_mul_f32_e32 v46, 0.5, v1
	v_pk_mul_f32 v[112:113], v[40:41], v[112:113] op_sel_hi:[0,1]
	v_pk_mul_f32 v[114:115], v[40:41], v[114:115] op_sel_hi:[0,1]
	v_pk_mul_f32 v[130:131], v[0:1], v[134:135] op_sel_hi:[0,1]
	v_pk_mul_f32 v[132:133], v[0:1], v[136:137] op_sel_hi:[0,1]
	v_mul_f32_e32 v2, 0.5, v2
	v_pk_fma_f32 v[110:111], v[114:115], v[128:129], v[110:111]
	v_pk_fma_f32 v[108:109], v[112:113], v[126:127], v[108:109]
	v_pk_fma_f32 v[114:115], v[132:133], v[128:129], v[140:141]
	v_pk_fma_f32 v[112:113], v[130:131], v[126:127], v[138:139]
	v_pk_mul_f32 v[130:131], v[46:47], v[158:159] op_sel_hi:[0,1]
	v_pk_mul_f32 v[132:133], v[46:47], v[160:161] op_sel_hi:[0,1]
	v_pk_mul_f32 v[134:135], v[2:3], v[162:163] op_sel_hi:[0,1]
	v_pk_mul_f32 v[136:137], v[2:3], v[164:165] op_sel_hi:[0,1]
	global_store_dwordx4 v[28:29], v[108:111], off nt
	global_store_dwordx4 v[30:31], v[112:115], off nt
	v_lshlrev_b32_e32 v138, 16, v82
	v_pk_fma_f32 v[110:111], v[128:129], v[132:133], v[144:145]
	v_pk_fma_f32 v[108:109], v[126:127], v[130:131], v[142:143]
	v_pk_fma_f32 v[114:115], v[128:129], v[136:137], v[148:149]
	v_pk_fma_f32 v[112:113], v[126:127], v[134:135], v[146:147]
	global_store_dwordx4 v[32:33], v[108:111], off nt
	global_store_dwordx4 v[34:35], v[112:115], off nt
	s_nop 0
	v_lshlrev_b32_e32 v126, 16, v76
	v_and_b32_e32 v127, 0xffff0000, v76
	v_lshlrev_b32_e32 v128, 16, v77
	v_and_b32_e32 v129, 0xffff0000, v77
	v_mov_b32_e32 v76, v93
	v_mov_b32_e32 v77, v97
	v_mov_b32_e32 v93, v96
	v_lshlrev_b32_e32 v130, 16, v78
	v_and_b32_e32 v131, 0xffff0000, v78
	v_lshlrev_b32_e32 v132, 16, v79
	v_and_b32_e32 v133, 0xffff0000, v79
	v_lshlrev_b32_e32 v134, 16, v80
	v_and_b32_e32 v135, 0xffff0000, v80
	v_lshlrev_b32_e32 v136, 16, v81
	v_and_b32_e32 v137, 0xffff0000, v81
	v_and_b32_e32 v139, 0xffff0000, v82
	v_lshlrev_b32_e32 v140, 16, v83
	v_and_b32_e32 v141, 0xffff0000, v83
	v_mov_b32_e32 v78, v95
	v_mov_b32_e32 v79, v99
	v_mov_b32_e32 v95, v98
	v_mov_b32_e32 v80, v101
	v_mov_b32_e32 v81, v103
	v_mov_b32_e32 v82, v105
	v_mov_b32_e32 v83, v107
	v_mov_b32_e32 v101, v102
	v_mov_b32_e32 v105, v106
	v_pk_mul_f32 v[96:97], v[40:41], v[76:77] op_sel_hi:[0,1]
	v_pk_mul_f32 v[76:77], v[40:41], v[92:93] op_sel_hi:[0,1]
	v_pk_mul_f32 v[92:93], v[0:1], v[78:79] op_sel_hi:[0,1]
	v_pk_mul_f32 v[94:95], v[0:1], v[94:95] op_sel_hi:[0,1]
	v_pk_mul_f32 v[98:99], v[46:47], v[80:81] op_sel_hi:[0,1]
	v_pk_mul_f32 v[100:101], v[46:47], v[100:101] op_sel_hi:[0,1]
	v_pk_mul_f32 v[102:103], v[2:3], v[82:83] op_sel_hi:[0,1]
	v_pk_mul_f32 v[104:105], v[2:3], v[104:105] op_sel_hi:[0,1]
	v_pk_mul_f32 v[84:85], v[46:47], v[84:85] op_sel_hi:[0,1]
	v_pk_mul_f32 v[86:87], v[2:3], v[86:87] op_sel_hi:[0,1]
	v_mov_b32_e32 v36, v41
	v_mov_b32_e32 v42, v47
	s_add_i32 s9, s9, s12
	s_cmpk_lt_i32 s9, 0x4000
	v_pk_mul_f32 v[106:107], v[222:223], v[226:227]
	v_pk_mul_f32 v[108:109], v[220:221], v[224:225]
	v_pk_fma_f32 v[78:79], v[96:97], v[106:107], v[128:129]
	v_pk_fma_f32 v[76:77], v[76:77], v[108:109], v[126:127]
	v_pk_fma_f32 v[80:81], v[94:95], v[108:109], v[130:131]
	v_pk_fma_f32 v[82:83], v[92:93], v[106:107], v[132:133]
	v_pk_fma_f32 v[92:93], v[100:101], v[108:109], v[134:135]
	v_pk_fma_f32 v[94:95], v[98:99], v[106:107], v[136:137]
	v_pk_fma_f32 v[96:97], v[108:109], v[104:105], v[138:139]
	v_pk_fma_f32 v[98:99], v[106:107], v[102:103], v[140:141]
	global_store_dwordx4 v[28:29], v[76:79], off offset:1024 nt
	global_store_dwordx4 v[30:31], v[80:83], off offset:1024 nt
	global_store_dwordx4 v[32:33], v[92:95], off offset:1024 nt
	global_store_dwordx4 v[34:35], v[96:99], off offset:1024 nt
	s_nop 0
	v_lshlrev_b32_e32 v92, 16, v48
	v_and_b32_e32 v93, 0xffff0000, v48
	v_lshlrev_b32_e32 v48, 16, v49
	v_and_b32_e32 v49, 0xffff0000, v49
	v_lshlrev_b32_e32 v94, 16, v56
	v_and_b32_e32 v95, 0xffff0000, v56
	v_lshlrev_b32_e32 v96, 16, v57
	v_and_b32_e32 v97, 0xffff0000, v57
	v_lshlrev_b32_e32 v98, 16, v58
	v_and_b32_e32 v99, 0xffff0000, v58
	v_lshlrev_b32_e32 v100, 16, v59
	v_and_b32_e32 v101, 0xffff0000, v59
	v_pk_mul_f32 v[58:59], v[40:41], v[72:73] op_sel_hi:[0,1]
	v_pk_mul_f32 v[56:57], v[40:41], v[68:69] op_sel_hi:[0,1]
	v_lshlrev_b32_e32 v102, 16, v64
	v_and_b32_e32 v103, 0xffff0000, v64
	v_lshlrev_b32_e32 v64, 16, v65
	v_and_b32_e32 v65, 0xffff0000, v65
	v_pk_mul_f32 v[72:73], v[0:1], v[74:75] op_sel_hi:[0,1]
	v_pk_mul_f32 v[68:69], v[0:1], v[70:71] op_sel_hi:[0,1]
	v_pk_mul_f32 v[74:75], v[46:47], v[88:89] op_sel_hi:[0,1]
	v_pk_mul_f32 v[88:89], v[2:3], v[90:91] op_sel_hi:[0,1]
	v_pk_mul_f32 v[78:79], v[230:231], v[234:235]
	v_pk_mul_f32 v[76:77], v[228:229], v[232:233]
	v_pk_fma_f32 v[58:59], v[58:59], v[78:79], v[48:49]
	v_pk_fma_f32 v[56:57], v[56:57], v[76:77], v[92:93]
	v_pk_fma_f32 v[68:69], v[68:69], v[76:77], v[94:95]
	v_pk_fma_f32 v[70:71], v[72:73], v[78:79], v[96:97]
	v_pk_fma_f32 v[72:73], v[84:85], v[76:77], v[98:99]
	v_pk_fma_f32 v[74:75], v[74:75], v[78:79], v[100:101]
	v_pk_fma_f32 v[76:77], v[86:87], v[76:77], v[102:103]
	v_pk_fma_f32 v[78:79], v[88:89], v[78:79], v[64:65]
	global_store_dwordx4 v[28:29], v[56:59], off offset:2048 nt
	global_store_dwordx4 v[30:31], v[68:71], off offset:2048 nt
	global_store_dwordx4 v[32:33], v[72:75], off offset:2048 nt
	global_store_dwordx4 v[34:35], v[76:79], off offset:2048 nt
	s_nop 0
	v_lshlrev_b32_e32 v48, 16, v20
	v_and_b32_e32 v49, 0xffff0000, v20
	v_lshlrev_b32_e32 v20, 16, v21
	v_and_b32_e32 v21, 0xffff0000, v21
	v_lshlrev_b32_e32 v72, 16, v24
	v_and_b32_e32 v73, 0xffff0000, v24
	v_lshlrev_b32_e32 v74, 16, v25
	v_and_b32_e32 v75, 0xffff0000, v25
	v_lshlrev_b32_e32 v76, 16, v26
	v_and_b32_e32 v77, 0xffff0000, v26
	v_lshlrev_b32_e32 v78, 16, v27
	v_and_b32_e32 v79, 0xffff0000, v27
	v_pk_mul_f32 v[24:25], v[40:41], v[38:39] op_sel_hi:[0,1]
	v_pk_mul_f32 v[26:27], v[40:41], v[36:37] op_sel_hi:[0,1]
	v_pk_mul_f32 v[38:39], v[0:1], v[42:43] op_sel_hi:[0,1]
	v_pk_mul_f32 v[40:41], v[46:47], v[52:53] op_sel_hi:[0,1]
	v_pk_mul_f32 v[42:43], v[46:47], v[50:51] op_sel_hi:[0,1]
	v_lshlrev_b32_e32 v64, 16, v22
	v_and_b32_e32 v65, 0xffff0000, v22
	v_lshlrev_b32_e32 v22, 16, v23
	v_and_b32_e32 v23, 0xffff0000, v23
	v_pk_mul_f32 v[36:37], v[0:1], v[44:45] op_sel_hi:[0,1]
	v_pk_mul_f32 v[44:45], v[2:3], v[62:63] op_sel_hi:[0,1]
	v_pk_mul_f32 v[46:47], v[2:3], v[60:61] op_sel_hi:[0,1]
	v_pk_mul_f32 v[50:51], v[238:239], v[242:243]
	v_pk_mul_f32 v[52:53], v[236:237], v[240:241]
	v_pk_fma_f32 v[2:3], v[24:25], v[50:51], v[20:21]
	v_pk_fma_f32 v[0:1], v[26:27], v[52:53], v[48:49]
	v_pk_fma_f32 v[20:21], v[38:39], v[52:53], v[64:65]
	v_pk_fma_f32 v[22:23], v[36:37], v[50:51], v[22:23]
	v_pk_fma_f32 v[24:25], v[42:43], v[52:53], v[72:73]
	v_pk_fma_f32 v[26:27], v[40:41], v[50:51], v[74:75]
	v_pk_fma_f32 v[36:37], v[46:47], v[52:53], v[76:77]
	v_pk_fma_f32 v[38:39], v[44:45], v[50:51], v[78:79]
	global_store_dwordx4 v[28:29], v[0:3], off offset:3072 nt
	global_store_dwordx4 v[30:31], v[20:23], off offset:3072 nt
	global_store_dwordx4 v[32:33], v[24:27], off offset:3072 nt
	global_store_dwordx4 v[34:35], v[36:39], off offset:3072 nt
	s_cbranch_scc1 .LBB0_1103
